# projection and gate K-loops: first K-iteration peeled with srcC=0 on each accumulator's first MFMA; the 32 zeroing MFMAs at the end of their epilogues removed (on top of v14)
# baseline (speedup 1.0000x reference)
.LBB0_110:
	s_add_u32 vcc_lo, s78, 0x160080
	s_addc_u32 vcc_hi, s79, 0
	s_add_u32 s84, s76, 0x100
	s_addc_u32 s85, s77, 0
	s_mov_b32 s93, -2
	s_add_u32 s72, vcc_lo, 0xffea0080
	s_addc_u32 s73, vcc_hi, -1
	s_add_i32 s95, 0, 0x10000
	s_cmp_eq_u32 s93, 12
	s_cselect_b32 s79, s1, s73
	s_cselect_b32 s78, s0, s72
	v_add_u32_e32 v26, s95, v186
	s_cselect_b32 s77, s89, s85
	s_cselect_b32 s76, s88, s84
	s_add_i32 s12, 0, 0x14000
	ds_read_b128 v[36:39], v26
	ds_read_b128 v[56:59], v26 offset:1024
	ds_read_b128 v[84:87], v26 offset:2048
	ds_read_b128 v[104:107], v26 offset:3072
	v_add_u32_e32 v26, s12, v186
	ds_read_b128 v[124:127], v26
	ds_read_b128 v[144:147], v26 offset:1024
	ds_read_b128 v[156:159], v26 offset:2048
	ds_read_b128 v[180:183], v26 offset:3072
	v_lshl_add_u64 v[226:227], vcc, 0, v[176:177]
	s_add_i32 m0, s17, 0xc000
	ds_read_b128 v[190:193], v188
	ds_read_b128 v[194:197], v188 offset:1024
	ds_read_b128 v[198:201], v188 offset:2048
	ds_read_b128 v[202:205], v188 offset:3072
	ds_read_b128 v[206:209], v188 offset:4096
	ds_read_b128 v[210:213], v188 offset:5120
	ds_read_b128 v[214:217], v188 offset:6144
	ds_read_b128 v[218:221], v188 offset:7168
	global_load_lds_dwordx4 v[226:227], off
	v_lshl_add_u64 v[226:227], vcc, 0, v[178:179]
	s_add_i32 m0, s17, 0xe000
	s_nop 0
	global_load_lds_dwordx4 v[226:227], off
	s_waitcnt vmcnt(8)
	s_waitcnt lgkmcnt(0)
	s_setprio 1
	s_barrier
	v_mfma_f32_16x16x32_bf16 v[148:151], v[36:39], v[190:193], 0
	v_mfma_f32_16x16x32_bf16 v[152:155], v[84:87], v[190:193], 0
	v_mfma_f32_16x16x32_bf16 v[128:131], v[36:39], v[198:201], 0
	v_mfma_f32_16x16x32_bf16 v[132:135], v[84:87], v[198:201], 0
	v_mfma_f32_16x16x32_bf16 v[108:111], v[36:39], v[206:209], 0
	v_mfma_f32_16x16x32_bf16 v[112:115], v[84:87], v[206:209], 0
	v_mfma_f32_16x16x32_bf16 v[88:91], v[36:39], v[214:217], 0
	v_mfma_f32_16x16x32_bf16 v[92:95], v[84:87], v[214:217], 0
	v_mfma_f32_16x16x32_bf16 v[148:151], v[56:59], v[194:197], v[148:151]
	v_mfma_f32_16x16x32_bf16 v[152:155], v[104:107], v[194:197], v[152:155]
	v_mfma_f32_16x16x32_bf16 v[128:131], v[56:59], v[202:205], v[128:131]
	v_mfma_f32_16x16x32_bf16 v[132:135], v[104:107], v[202:205], v[132:135]
	v_mfma_f32_16x16x32_bf16 v[108:111], v[56:59], v[210:213], v[108:111]
	v_mfma_f32_16x16x32_bf16 v[112:115], v[104:107], v[210:213], v[112:115]
	v_mfma_f32_16x16x32_bf16 v[88:91], v[56:59], v[218:221], v[88:91]
	v_mfma_f32_16x16x32_bf16 v[92:95], v[104:107], v[218:221], v[92:95]
	s_setprio 0
	s_setprio 1
	v_mfma_f32_16x16x32_bf16 v[140:143], v[124:127], v[190:193], 0
	v_mfma_f32_16x16x32_bf16 v[136:139], v[156:159], v[190:193], 0
	v_mfma_f32_16x16x32_bf16 v[120:123], v[124:127], v[198:201], 0
	v_mfma_f32_16x16x32_bf16 v[116:119], v[156:159], v[198:201], 0
	v_mfma_f32_16x16x32_bf16 v[100:103], v[124:127], v[206:209], 0
	v_mfma_f32_16x16x32_bf16 v[96:99], v[156:159], v[206:209], 0
	v_mfma_f32_16x16x32_bf16 v[80:83], v[124:127], v[214:217], 0
	v_mfma_f32_16x16x32_bf16 v[76:79], v[156:159], v[214:217], 0
	v_mfma_f32_16x16x32_bf16 v[140:143], v[144:147], v[194:197], v[140:143]
	v_mfma_f32_16x16x32_bf16 v[136:139], v[180:183], v[194:197], v[136:139]
	v_mfma_f32_16x16x32_bf16 v[120:123], v[144:147], v[202:205], v[120:123]
	v_mfma_f32_16x16x32_bf16 v[116:119], v[180:183], v[202:205], v[116:119]
	v_mfma_f32_16x16x32_bf16 v[100:103], v[144:147], v[210:213], v[100:103]
	v_mfma_f32_16x16x32_bf16 v[96:99], v[180:183], v[210:213], v[96:99]
	v_mfma_f32_16x16x32_bf16 v[80:83], v[144:147], v[218:221], v[80:83]
	v_mfma_f32_16x16x32_bf16 v[76:79], v[180:183], v[218:221], v[76:79]
	s_barrier
	s_setprio 0
	s_add_i32 s72, s95, s16
	v_lshl_add_u64 v[226:227], s[76:77], 0, v[164:165]
	s_mov_b32 m0, s72
	ds_read_b128 v[190:193], v188 offset:16384
	ds_read_b128 v[194:197], v188 offset:17408
	ds_read_b128 v[198:201], v188 offset:18432
	ds_read_b128 v[202:205], v188 offset:19456
	ds_read_b128 v[206:209], v188 offset:20480
	ds_read_b128 v[210:213], v188 offset:21504
	ds_read_b128 v[214:217], v188 offset:22528
	ds_read_b128 v[218:221], v188 offset:23552
	global_load_lds_dwordx4 v[226:227], off
	s_add_i32 m0, s72, 0x2000
	s_add_u32 s72, s76, 0x40000
	v_lshl_add_u64 v[228:229], s[76:77], 0, v[160:161]
	s_addc_u32 s73, s77, 0
	s_add_i32 s12, s12, s16
	global_load_lds_dwordx4 v[228:229], off
	v_lshl_add_u64 v[230:231], s[72:73], 0, v[164:165]
	s_mov_b32 m0, s12
	v_lshl_add_u64 v[232:233], s[78:79], 0, v[162:163]
	global_load_lds_dwordx4 v[230:231], off
	v_lshl_add_u64 v[230:231], s[72:73], 0, v[160:161]
	s_add_i32 m0, s12, 0x2000
	s_nop 0
	global_load_lds_dwordx4 v[230:231], off
	v_lshl_add_u64 v[230:231], s[78:79], 0, v[166:167]
	s_mov_b32 m0, s17
	s_nop 0
	global_load_lds_dwordx4 v[230:231], off
	s_mov_b32 m0, s46
	s_nop 0
	global_load_lds_dwordx4 v[232:233], off
	s_waitcnt vmcnt(8)
	s_waitcnt lgkmcnt(0)
	s_setprio 1
	s_barrier
	v_mfma_f32_16x16x32_bf16 v[68:71], v[36:39], v[190:193], 0
	v_mfma_f32_16x16x32_bf16 v[72:75], v[84:87], v[190:193], 0
	v_mfma_f32_16x16x32_bf16 v[48:51], v[36:39], v[198:201], 0
	v_mfma_f32_16x16x32_bf16 v[52:55], v[84:87], v[198:201], 0
	v_mfma_f32_16x16x32_bf16 v[28:31], v[36:39], v[206:209], 0
	v_mfma_f32_16x16x32_bf16 v[32:35], v[84:87], v[206:209], 0
	v_mfma_f32_16x16x32_bf16 v[10:13], v[36:39], v[214:217], 0
	v_mfma_f32_16x16x32_bf16 v[14:17], v[84:87], v[214:217], 0
	v_mfma_f32_16x16x32_bf16 v[68:71], v[56:59], v[194:197], v[68:71]
	v_mfma_f32_16x16x32_bf16 v[72:75], v[104:107], v[194:197], v[72:75]
	v_mfma_f32_16x16x32_bf16 v[48:51], v[56:59], v[202:205], v[48:51]
	v_mfma_f32_16x16x32_bf16 v[52:55], v[104:107], v[202:205], v[52:55]
	v_mfma_f32_16x16x32_bf16 v[28:31], v[56:59], v[210:213], v[28:31]
	v_mfma_f32_16x16x32_bf16 v[32:35], v[104:107], v[210:213], v[32:35]
	v_mfma_f32_16x16x32_bf16 v[10:13], v[56:59], v[218:221], v[10:13]
	v_mfma_f32_16x16x32_bf16 v[14:17], v[104:107], v[218:221], v[14:17]
	s_setprio 0
	s_setprio 1
	v_mfma_f32_16x16x32_bf16 v[44:47], v[124:127], v[198:201], 0
	v_mfma_f32_16x16x32_bf16 v[40:43], v[156:159], v[198:201], 0
	v_mfma_f32_16x16x32_bf16 v[22:25], v[124:127], v[206:209], 0
	v_mfma_f32_16x16x32_bf16 v[18:21], v[156:159], v[206:209], 0
	v_mfma_f32_16x16x32_bf16 v[2:5], v[124:127], v[214:217], 0
	v_mfma_f32_16x16x32_bf16 v[6:9], v[156:159], v[214:217], 0
	v_mfma_f32_16x16x32_bf16 v[36:39], v[124:127], v[190:193], 0
	v_mfma_f32_16x16x32_bf16 v[56:59], v[156:159], v[190:193], 0
	v_mfma_f32_16x16x32_bf16 v[44:47], v[144:147], v[202:205], v[44:47]
	v_mfma_f32_16x16x32_bf16 v[40:43], v[180:183], v[202:205], v[40:43]
	v_mfma_f32_16x16x32_bf16 v[22:25], v[144:147], v[210:213], v[22:25]
	v_mfma_f32_16x16x32_bf16 v[18:21], v[180:183], v[210:213], v[18:21]
	v_mfma_f32_16x16x32_bf16 v[2:5], v[144:147], v[218:221], v[2:5]
	v_mfma_f32_16x16x32_bf16 v[6:9], v[180:183], v[218:221], v[6:9]
	v_mfma_f32_16x16x32_bf16 v[36:39], v[144:147], v[194:197], v[36:39]
	v_mfma_f32_16x16x32_bf16 v[56:59], v[180:183], v[194:197], v[56:59]
	s_barrier
	s_setprio 0
	s_add_i32 s12, 0, 0x18000
	v_add_u32_e32 v26, s12, v186
	s_add_i32 s95, 0, 0x1c000
	ds_read_b128 v[60:63], v26
	ds_read_b128 v[64:67], v26 offset:1024
	ds_read_b128 v[84:87], v26 offset:2048
	ds_read_b128 v[104:107], v26 offset:3072
	v_add_u32_e32 v26, s95, v186
	ds_read_b128 v[124:127], v26
	ds_read_b128 v[144:147], v26 offset:1024
	ds_read_b128 v[156:159], v26 offset:2048
	ds_read_b128 v[180:183], v26 offset:3072
	s_add_u32 s72, s78, 0x160000
	s_addc_u32 s73, s79, 0
	s_mov_b32 m0, s47
	v_lshl_add_u64 v[234:235], s[72:73], 0, v[166:167]
	ds_read_b128 v[190:193], v188 offset:32768
	ds_read_b128 v[194:197], v188 offset:33792
	ds_read_b128 v[198:201], v188 offset:34816
	ds_read_b128 v[202:205], v188 offset:35840
	ds_read_b128 v[206:209], v188 offset:36864
	ds_read_b128 v[210:213], v188 offset:37888
	ds_read_b128 v[214:217], v188 offset:38912
	ds_read_b128 v[218:221], v188 offset:39936
	global_load_lds_dwordx4 v[234:235], off
	v_lshl_add_u64 v[234:235], s[72:73], 0, v[162:163]
	s_mov_b32 m0, s8
	s_nop 0
	global_load_lds_dwordx4 v[234:235], off
	s_waitcnt vmcnt(8)
	s_waitcnt lgkmcnt(0)
	s_setprio 1
	s_barrier
	v_mfma_f32_16x16x32_bf16 v[148:151], v[60:63], v[190:193], v[148:151]
	v_mfma_f32_16x16x32_bf16 v[152:155], v[84:87], v[190:193], v[152:155]
	v_mfma_f32_16x16x32_bf16 v[128:131], v[60:63], v[198:201], v[128:131]
	v_mfma_f32_16x16x32_bf16 v[132:135], v[84:87], v[198:201], v[132:135]
	v_mfma_f32_16x16x32_bf16 v[108:111], v[60:63], v[206:209], v[108:111]
	v_mfma_f32_16x16x32_bf16 v[112:115], v[84:87], v[206:209], v[112:115]
	v_mfma_f32_16x16x32_bf16 v[88:91], v[60:63], v[214:217], v[88:91]
	v_mfma_f32_16x16x32_bf16 v[92:95], v[84:87], v[214:217], v[92:95]
	v_mfma_f32_16x16x32_bf16 v[148:151], v[64:67], v[194:197], v[148:151]
	v_mfma_f32_16x16x32_bf16 v[152:155], v[104:107], v[194:197], v[152:155]
	v_mfma_f32_16x16x32_bf16 v[128:131], v[64:67], v[202:205], v[128:131]
	v_mfma_f32_16x16x32_bf16 v[132:135], v[104:107], v[202:205], v[132:135]
	v_mfma_f32_16x16x32_bf16 v[108:111], v[64:67], v[210:213], v[108:111]
	v_mfma_f32_16x16x32_bf16 v[112:115], v[104:107], v[210:213], v[112:115]
	v_mfma_f32_16x16x32_bf16 v[88:91], v[64:67], v[218:221], v[88:91]
	v_mfma_f32_16x16x32_bf16 v[92:95], v[104:107], v[218:221], v[92:95]
	s_setprio 0
	s_setprio 1
	v_mfma_f32_16x16x32_bf16 v[140:143], v[124:127], v[190:193], v[140:143]
	v_mfma_f32_16x16x32_bf16 v[136:139], v[156:159], v[190:193], v[136:139]
	v_mfma_f32_16x16x32_bf16 v[120:123], v[124:127], v[198:201], v[120:123]
	v_mfma_f32_16x16x32_bf16 v[116:119], v[156:159], v[198:201], v[116:119]
	v_mfma_f32_16x16x32_bf16 v[100:103], v[124:127], v[206:209], v[100:103]
	v_mfma_f32_16x16x32_bf16 v[96:99], v[156:159], v[206:209], v[96:99]
	v_mfma_f32_16x16x32_bf16 v[80:83], v[124:127], v[214:217], v[80:83]
	v_mfma_f32_16x16x32_bf16 v[76:79], v[156:159], v[214:217], v[76:79]
	v_mfma_f32_16x16x32_bf16 v[140:143], v[144:147], v[194:197], v[140:143]
	v_mfma_f32_16x16x32_bf16 v[136:139], v[180:183], v[194:197], v[136:139]
	v_mfma_f32_16x16x32_bf16 v[120:123], v[144:147], v[202:205], v[120:123]
	v_mfma_f32_16x16x32_bf16 v[116:119], v[180:183], v[202:205], v[116:119]
	v_mfma_f32_16x16x32_bf16 v[100:103], v[144:147], v[210:213], v[100:103]
	v_mfma_f32_16x16x32_bf16 v[96:99], v[180:183], v[210:213], v[96:99]
	v_mfma_f32_16x16x32_bf16 v[80:83], v[144:147], v[218:221], v[80:83]
	v_mfma_f32_16x16x32_bf16 v[76:79], v[180:183], v[218:221], v[76:79]
	s_barrier
	s_setprio 0
	s_add_i32 s12, s12, s16
	v_lshl_add_u64 v[226:227], v[226:227], 0, s[82:83]
	s_mov_b32 m0, s12
	ds_read_b128 v[190:193], v188 offset:49152
	ds_read_b128 v[194:197], v188 offset:50176
	ds_read_b128 v[198:201], v188 offset:51200
	ds_read_b128 v[202:205], v188 offset:52224
	ds_read_b128 v[206:209], v188 offset:53248
	ds_read_b128 v[210:213], v188 offset:54272
	ds_read_b128 v[214:217], v188 offset:55296
	ds_read_b128 v[218:221], v188 offset:56320
	global_load_lds_dwordx4 v[226:227], off
	s_add_i32 m0, s12, 0x2000
	s_add_u32 s72, s76, 0x40080
	v_lshl_add_u64 v[226:227], v[228:229], 0, s[82:83]
	s_addc_u32 s73, s77, 0
	s_add_i32 s12, s95, s16
	global_load_lds_dwordx4 v[226:227], off
	v_lshl_add_u64 v[226:227], s[72:73], 0, v[164:165]
	s_mov_b32 m0, s12
	s_nop 0
	global_load_lds_dwordx4 v[226:227], off
	v_lshl_add_u64 v[226:227], s[72:73], 0, v[160:161]
	s_add_i32 m0, s12, 0x2000
	s_nop 0
	global_load_lds_dwordx4 v[226:227], off
	v_lshl_add_u64 v[226:227], v[230:231], 0, s[82:83]
	s_mov_b32 m0, s22
	s_nop 0
	global_load_lds_dwordx4 v[226:227], off
	v_lshl_add_u64 v[226:227], v[232:233], 0, s[82:83]
	s_mov_b32 m0, s80
	s_nop 0
	global_load_lds_dwordx4 v[226:227], off
	s_waitcnt vmcnt(8)
	s_waitcnt lgkmcnt(0)
	s_setprio 1
	s_barrier
	v_mfma_f32_16x16x32_bf16 v[68:71], v[60:63], v[190:193], v[68:71]
	v_mfma_f32_16x16x32_bf16 v[72:75], v[84:87], v[190:193], v[72:75]
	v_mfma_f32_16x16x32_bf16 v[48:51], v[60:63], v[198:201], v[48:51]
	v_mfma_f32_16x16x32_bf16 v[52:55], v[84:87], v[198:201], v[52:55]
	v_mfma_f32_16x16x32_bf16 v[28:31], v[60:63], v[206:209], v[28:31]
	v_mfma_f32_16x16x32_bf16 v[32:35], v[84:87], v[206:209], v[32:35]
	v_mfma_f32_16x16x32_bf16 v[10:13], v[60:63], v[214:217], v[10:13]
	v_mfma_f32_16x16x32_bf16 v[14:17], v[84:87], v[214:217], v[14:17]
	v_mfma_f32_16x16x32_bf16 v[68:71], v[64:67], v[194:197], v[68:71]
	v_mfma_f32_16x16x32_bf16 v[72:75], v[104:107], v[194:197], v[72:75]
	v_mfma_f32_16x16x32_bf16 v[48:51], v[64:67], v[202:205], v[48:51]
	v_mfma_f32_16x16x32_bf16 v[52:55], v[104:107], v[202:205], v[52:55]
	v_mfma_f32_16x16x32_bf16 v[28:31], v[64:67], v[210:213], v[28:31]
	v_mfma_f32_16x16x32_bf16 v[32:35], v[104:107], v[210:213], v[32:35]
	v_mfma_f32_16x16x32_bf16 v[10:13], v[64:67], v[218:221], v[10:13]
	v_mfma_f32_16x16x32_bf16 v[14:17], v[104:107], v[218:221], v[14:17]
	s_setprio 0
	s_setprio 1
	v_mfma_f32_16x16x32_bf16 v[36:39], v[124:127], v[190:193], v[36:39]
	v_mfma_f32_16x16x32_bf16 v[64:67], v[144:147], v[194:197], v[36:39]
	v_mfma_f32_16x16x32_bf16 v[36:39], v[156:159], v[190:193], v[56:59]
	v_mfma_f32_16x16x32_bf16 v[60:63], v[180:183], v[194:197], v[36:39]
	v_mfma_f32_16x16x32_bf16 v[36:39], v[124:127], v[198:201], v[44:47]
	v_mfma_f32_16x16x32_bf16 v[44:47], v[144:147], v[202:205], v[36:39]
	v_mfma_f32_16x16x32_bf16 v[36:39], v[156:159], v[198:201], v[40:43]
	v_mfma_f32_16x16x32_bf16 v[22:25], v[124:127], v[206:209], v[22:25]
	v_mfma_f32_16x16x32_bf16 v[18:21], v[156:159], v[206:209], v[18:21]
	v_mfma_f32_16x16x32_bf16 v[2:5], v[124:127], v[214:217], v[2:5]
	v_mfma_f32_16x16x32_bf16 v[6:9], v[156:159], v[214:217], v[6:9]
	v_mfma_f32_16x16x32_bf16 v[40:43], v[180:183], v[202:205], v[36:39]
	v_mfma_f32_16x16x32_bf16 v[22:25], v[144:147], v[210:213], v[22:25]
	v_mfma_f32_16x16x32_bf16 v[18:21], v[180:183], v[210:213], v[18:21]
	v_mfma_f32_16x16x32_bf16 v[2:5], v[144:147], v[218:221], v[2:5]
	v_mfma_f32_16x16x32_bf16 v[6:9], v[180:183], v[218:221], v[6:9]
	s_barrier
	s_setprio 0
	s_add_i32 s93, s93, 2
	s_add_u32 vcc_lo, vcc_lo, 0x100
	s_addc_u32 vcc_hi, vcc_hi, 0
	s_add_u32 s84, s84, 0x100
	s_addc_u32 s85, s85, 0

.LBB0_194:
	v_mov_b32_e32 v26, v27
	v_mov_b32_e32 v28, v27
	v_mov_b32_e32 v29, v27
	v_mov_b64_e32 v[6:7], v[26:27]
	v_mov_b64_e32 v[8:9], v[28:29]
	s_mov_b64 s[0:1], -1
	s_andn2_b64 vcc, exec, s[40:41]
	s_waitcnt lgkmcnt(0)
	s_cbranch_vccnz .LBB0_107
	s_andn2_b64 vcc, exec, s[58:59]
	s_cbranch_vccnz .LBB0_106
	s_barrier
	s_branch .LBB0_106

.LBB0_207:
	s_xor_b64 s[38:39], s[38:39], -1
	s_add_u32 s90, s78, 0x20080
	s_addc_u32 s91, s79, 0
	s_add_u32 s76, s76, 0x100
	s_addc_u32 s77, s77, 0
	s_mov_b32 s78, -2
	s_add_u32 s72, s90, 0xfffe0080
	s_addc_u32 s73, s91, -1
	s_add_i32 s79, 0, 0x10000
	s_cmp_eq_u32 s78, 4
	s_cselect_b32 s95, s89, s73
	s_cselect_b32 s94, s88, s72
	s_cselect_b32 s93, s61, s77
	s_cselect_b32 s92, s60, s76
	s_add_i32 s72, 0, 0x14000
	v_add_u32_e32 v14, s79, v189
	v_add_u32_e32 v26, s72, v189
	ds_read_b128 v[2:5], v14
	ds_read_b128 v[6:9], v14 offset:1024
	ds_read_b128 v[10:13], v14 offset:2048
	ds_read_b128 v[14:17], v14 offset:3072
	ds_read_b128 v[18:21], v26
	ds_read_b128 v[22:25], v26 offset:1024
	ds_read_b128 v[192:195], v26 offset:2048
	ds_read_b128 v[196:199], v26 offset:3072
	v_lshl_add_u64 v[216:217], s[90:91], 0, v[166:167]
	s_add_i32 m0, s11, 0xc000
	ds_read_b128 v[178:181], v190
	ds_read_b128 v[182:185], v190 offset:1024
	ds_read_b128 v[200:203], v190 offset:2048
	ds_read_b128 v[204:207], v190 offset:3072
	ds_read_b128 v[208:211], v190 offset:4096
	ds_read_b128 v[212:215], v190 offset:5120
	ds_read_b128 v[226:229], v190 offset:6144
	ds_read_b128 v[230:233], v190 offset:7168
	global_load_lds_dwordx4 v[216:217], off
	v_lshl_add_u64 v[216:217], s[90:91], 0, v[176:177]
	s_add_i32 m0, s11, 0xe000
	s_nop 0
	global_load_lds_dwordx4 v[216:217], off
	s_waitcnt vmcnt(8)
	s_waitcnt lgkmcnt(0)
	s_setprio 1
	s_barrier
	v_mfma_scale_f32_16x16x128_f8f6f4 v[148:151], v[2:9], v[178:185], 0, v186, v186 op_sel_hi:[0,0,0]
	v_mfma_scale_f32_16x16x128_f8f6f4 v[152:155], v[10:17], v[178:185], 0, v186, v186 op_sel_hi:[0,0,0]
	v_mfma_scale_f32_16x16x128_f8f6f4 v[124:127], v[2:9], v[200:207], 0, v186, v186 op_sel_hi:[0,0,0]
	v_mfma_scale_f32_16x16x128_f8f6f4 v[128:131], v[10:17], v[200:207], 0, v186, v186 op_sel_hi:[0,0,0]
	v_mfma_scale_f32_16x16x128_f8f6f4 v[108:111], v[2:9], v[208:215], 0, v186, v186 op_sel_hi:[0,0,0]
	v_mfma_scale_f32_16x16x128_f8f6f4 v[112:115], v[10:17], v[208:215], 0, v186, v186 op_sel_hi:[0,0,0]
	v_mfma_scale_f32_16x16x128_f8f6f4 v[92:95], v[2:9], v[226:233], 0, v186, v186 op_sel_hi:[0,0,0]
	v_mfma_scale_f32_16x16x128_f8f6f4 v[96:99], v[10:17], v[226:233], 0, v186, v186 op_sel_hi:[0,0,0]
	s_setprio 0
	s_setprio 1
	v_mfma_scale_f32_16x16x128_f8f6f4 v[140:143], v[18:25], v[178:185], 0, v186, v186 op_sel_hi:[0,0,0]
	v_mfma_scale_f32_16x16x128_f8f6f4 v[144:147], v[192:199], v[178:185], 0, v186, v186 op_sel_hi:[0,0,0]
	v_mfma_scale_f32_16x16x128_f8f6f4 v[132:135], v[18:25], v[200:207], 0, v186, v186 op_sel_hi:[0,0,0]
	v_mfma_scale_f32_16x16x128_f8f6f4 v[136:139], v[192:199], v[200:207], 0, v186, v186 op_sel_hi:[0,0,0]
	v_mfma_scale_f32_16x16x128_f8f6f4 v[116:119], v[18:25], v[208:215], 0, v186, v186 op_sel_hi:[0,0,0]
	v_mfma_scale_f32_16x16x128_f8f6f4 v[120:123], v[192:199], v[208:215], 0, v186, v186 op_sel_hi:[0,0,0]
	v_mfma_scale_f32_16x16x128_f8f6f4 v[100:103], v[18:25], v[226:233], 0, v186, v186 op_sel_hi:[0,0,0]
	v_mfma_scale_f32_16x16x128_f8f6f4 v[104:107], v[192:199], v[226:233], 0, v186, v186 op_sel_hi:[0,0,0]
	s_barrier
	s_setprio 0
	s_add_i32 s73, s79, s8
	v_lshl_add_u64 v[178:179], s[92:93], 0, v[158:159]
	s_mov_b32 m0, s73
	ds_read_b128 v[200:203], v190 offset:16384
	ds_read_b128 v[204:207], v190 offset:17408
	ds_read_b128 v[208:211], v190 offset:18432
	ds_read_b128 v[212:215], v190 offset:19456
	ds_read_b128 v[226:229], v190 offset:20480
	ds_read_b128 v[230:233], v190 offset:21504
	ds_read_b128 v[234:237], v190 offset:22528
	ds_read_b128 v[238:241], v190 offset:23552
	global_load_lds_dwordx4 v[178:179], off
	s_add_i32 m0, s73, 0x2000
	s_add_u32 s80, s92, 0x20000
	v_lshl_add_u64 v[180:181], s[92:93], 0, v[162:163]
	s_addc_u32 s81, s93, 0
	s_add_i32 s72, s72, s8
	global_load_lds_dwordx4 v[180:181], off
	v_lshl_add_u64 v[182:183], s[80:81], 0, v[158:159]
	s_mov_b32 m0, s72
	v_lshl_add_u64 v[184:185], s[94:95], 0, v[160:161]
	global_load_lds_dwordx4 v[182:183], off
	v_lshl_add_u64 v[182:183], s[80:81], 0, v[162:163]
	s_add_i32 m0, s72, 0x2000
	s_nop 0
	global_load_lds_dwordx4 v[182:183], off
	v_lshl_add_u64 v[182:183], s[94:95], 0, v[156:157]
	s_mov_b32 m0, s11
	s_nop 0
	global_load_lds_dwordx4 v[182:183], off
	s_mov_b32 m0, s16
	s_nop 0
	global_load_lds_dwordx4 v[184:185], off
	s_waitcnt vmcnt(8)
	s_waitcnt lgkmcnt(0)
	s_setprio 1
	s_barrier
	v_mfma_scale_f32_16x16x128_f8f6f4 v[76:79], v[2:9], v[200:207], 0, v186, v186 op_sel_hi:[0,0,0]
	v_mfma_scale_f32_16x16x128_f8f6f4 v[80:83], v[10:17], v[200:207], 0, v186, v186 op_sel_hi:[0,0,0]
	v_mfma_scale_f32_16x16x128_f8f6f4 v[60:63], v[2:9], v[208:215], 0, v186, v186 op_sel_hi:[0,0,0]
	v_mfma_scale_f32_16x16x128_f8f6f4 v[64:67], v[10:17], v[208:215], 0, v186, v186 op_sel_hi:[0,0,0]
	v_mfma_scale_f32_16x16x128_f8f6f4 v[44:47], v[2:9], v[226:233], 0, v186, v186 op_sel_hi:[0,0,0]
	v_mfma_scale_f32_16x16x128_f8f6f4 v[48:51], v[10:17], v[226:233], 0, v186, v186 op_sel_hi:[0,0,0]
	v_mfma_scale_f32_16x16x128_f8f6f4 v[28:31], v[2:9], v[234:241], 0, v186, v186 op_sel_hi:[0,0,0]
	v_mfma_scale_f32_16x16x128_f8f6f4 v[32:35], v[10:17], v[234:241], 0, v186, v186 op_sel_hi:[0,0,0]
	s_setprio 0
	s_setprio 1
	v_mfma_scale_f32_16x16x128_f8f6f4 v[84:87], v[18:25], v[200:207], 0, v186, v186 op_sel_hi:[0,0,0]
	v_mfma_scale_f32_16x16x128_f8f6f4 v[88:91], v[192:199], v[200:207], 0, v186, v186 op_sel_hi:[0,0,0]
	v_mfma_scale_f32_16x16x128_f8f6f4 v[68:71], v[18:25], v[208:215], 0, v186, v186 op_sel_hi:[0,0,0]
	v_mfma_scale_f32_16x16x128_f8f6f4 v[72:75], v[192:199], v[208:215], 0, v186, v186 op_sel_hi:[0,0,0]
	v_mfma_scale_f32_16x16x128_f8f6f4 v[52:55], v[18:25], v[226:233], 0, v186, v186 op_sel_hi:[0,0,0]
	v_mfma_scale_f32_16x16x128_f8f6f4 v[56:59], v[192:199], v[226:233], 0, v186, v186 op_sel_hi:[0,0,0]
	v_mfma_scale_f32_16x16x128_f8f6f4 v[36:39], v[18:25], v[234:241], 0, v186, v186 op_sel_hi:[0,0,0]
	v_mfma_scale_f32_16x16x128_f8f6f4 v[40:43], v[192:199], v[234:241], 0, v186, v186 op_sel_hi:[0,0,0]
	s_barrier
	s_setprio 0
	s_add_i32 s79, 0, 0x18000
	s_add_i32 s72, 0, 0x1c000
	v_add_u32_e32 v2, s79, v189
	v_add_u32_e32 v22, s72, v189
	ds_read_b128 v[10:13], v2
	ds_read_b128 v[14:17], v2 offset:1024
	ds_read_b128 v[192:195], v2 offset:2048
	ds_read_b128 v[196:199], v2 offset:3072
	ds_read_b128 v[2:5], v22
	ds_read_b128 v[6:9], v22 offset:1024
	ds_read_b128 v[18:21], v22 offset:2048
	ds_read_b128 v[22:25], v22 offset:3072
	s_add_u32 s80, s94, 0x20000
	s_addc_u32 s81, s95, 0
	s_mov_b32 m0, s17
	v_lshl_add_u64 v[216:217], s[80:81], 0, v[156:157]
	ds_read_b128 v[200:203], v190 offset:32768
	ds_read_b128 v[204:207], v190 offset:33792
	ds_read_b128 v[208:211], v190 offset:34816
	ds_read_b128 v[212:215], v190 offset:35840
	ds_read_b128 v[226:229], v190 offset:36864
	ds_read_b128 v[230:233], v190 offset:37888
	ds_read_b128 v[234:237], v190 offset:38912
	ds_read_b128 v[238:241], v190 offset:39936
	global_load_lds_dwordx4 v[216:217], off
	v_lshl_add_u64 v[216:217], s[80:81], 0, v[160:161]
	s_mov_b32 m0, s22
	s_nop 0
	global_load_lds_dwordx4 v[216:217], off
	s_waitcnt vmcnt(8)
	s_waitcnt lgkmcnt(0)
	s_setprio 1
	s_barrier
	v_mfma_scale_f32_16x16x128_f8f6f4 v[148:151], v[10:17], v[200:207], v[148:151], v186, v186 op_sel_hi:[0,0,0]
	v_mfma_scale_f32_16x16x128_f8f6f4 v[152:155], v[192:199], v[200:207], v[152:155], v186, v186 op_sel_hi:[0,0,0]
	v_mfma_scale_f32_16x16x128_f8f6f4 v[124:127], v[10:17], v[208:215], v[124:127], v186, v186 op_sel_hi:[0,0,0]
	v_mfma_scale_f32_16x16x128_f8f6f4 v[128:131], v[192:199], v[208:215], v[128:131], v186, v186 op_sel_hi:[0,0,0]
	v_mfma_scale_f32_16x16x128_f8f6f4 v[108:111], v[10:17], v[226:233], v[108:111], v186, v186 op_sel_hi:[0,0,0]
	v_mfma_scale_f32_16x16x128_f8f6f4 v[112:115], v[192:199], v[226:233], v[112:115], v186, v186 op_sel_hi:[0,0,0]
	v_mfma_scale_f32_16x16x128_f8f6f4 v[92:95], v[10:17], v[234:241], v[92:95], v186, v186 op_sel_hi:[0,0,0]
	v_mfma_scale_f32_16x16x128_f8f6f4 v[96:99], v[192:199], v[234:241], v[96:99], v186, v186 op_sel_hi:[0,0,0]
	s_setprio 0
	s_setprio 1
	v_mfma_scale_f32_16x16x128_f8f6f4 v[140:143], v[2:9], v[200:207], v[140:143], v186, v186 op_sel_hi:[0,0,0]
	v_mfma_scale_f32_16x16x128_f8f6f4 v[144:147], v[18:25], v[200:207], v[144:147], v186, v186 op_sel_hi:[0,0,0]
	v_mfma_scale_f32_16x16x128_f8f6f4 v[132:135], v[2:9], v[208:215], v[132:135], v186, v186 op_sel_hi:[0,0,0]
	v_mfma_scale_f32_16x16x128_f8f6f4 v[136:139], v[18:25], v[208:215], v[136:139], v186, v186 op_sel_hi:[0,0,0]
	v_mfma_scale_f32_16x16x128_f8f6f4 v[116:119], v[2:9], v[226:233], v[116:119], v186, v186 op_sel_hi:[0,0,0]
	v_mfma_scale_f32_16x16x128_f8f6f4 v[120:123], v[18:25], v[226:233], v[120:123], v186, v186 op_sel_hi:[0,0,0]
	v_mfma_scale_f32_16x16x128_f8f6f4 v[100:103], v[2:9], v[234:241], v[100:103], v186, v186 op_sel_hi:[0,0,0]
	v_mfma_scale_f32_16x16x128_f8f6f4 v[104:107], v[18:25], v[234:241], v[104:107], v186, v186 op_sel_hi:[0,0,0]
	s_barrier
	s_setprio 0
	s_add_i32 s73, s79, s8
	v_lshl_add_u64 v[178:179], v[178:179], 0, s[82:83]
	s_mov_b32 m0, s73
	ds_read_b128 v[200:203], v190 offset:49152
	ds_read_b128 v[204:207], v190 offset:50176
	ds_read_b128 v[208:211], v190 offset:51200
	ds_read_b128 v[212:215], v190 offset:52224
	ds_read_b128 v[226:229], v190 offset:53248
	ds_read_b128 v[230:233], v190 offset:54272
	ds_read_b128 v[234:237], v190 offset:55296
	ds_read_b128 v[238:241], v190 offset:56320
	global_load_lds_dwordx4 v[178:179], off
	s_add_i32 m0, s73, 0x2000
	s_add_u32 s80, s92, 0x20080
	v_lshl_add_u64 v[178:179], v[180:181], 0, s[82:83]
	s_addc_u32 s81, s93, 0
	s_add_i32 s72, s72, s8
	global_load_lds_dwordx4 v[178:179], off
	v_lshl_add_u64 v[178:179], s[80:81], 0, v[158:159]
	s_mov_b32 m0, s72
	s_nop 0
	global_load_lds_dwordx4 v[178:179], off
	v_lshl_add_u64 v[178:179], s[80:81], 0, v[162:163]
	s_add_i32 m0, s72, 0x2000
	s_nop 0
	global_load_lds_dwordx4 v[178:179], off
	v_lshl_add_u64 v[178:179], v[182:183], 0, s[82:83]
	s_mov_b32 m0, s26
	s_nop 0
	global_load_lds_dwordx4 v[178:179], off
	v_lshl_add_u64 v[178:179], v[184:185], 0, s[82:83]
	s_mov_b32 m0, s27
	s_nop 0
	global_load_lds_dwordx4 v[178:179], off
	s_waitcnt vmcnt(8)
	s_waitcnt lgkmcnt(0)
	s_setprio 1
	s_barrier
	v_mfma_scale_f32_16x16x128_f8f6f4 v[76:79], v[10:17], v[200:207], v[76:79], v186, v186 op_sel_hi:[0,0,0]
	v_mfma_scale_f32_16x16x128_f8f6f4 v[80:83], v[192:199], v[200:207], v[80:83], v186, v186 op_sel_hi:[0,0,0]
	v_mfma_scale_f32_16x16x128_f8f6f4 v[60:63], v[10:17], v[208:215], v[60:63], v186, v186 op_sel_hi:[0,0,0]
	v_mfma_scale_f32_16x16x128_f8f6f4 v[64:67], v[192:199], v[208:215], v[64:67], v186, v186 op_sel_hi:[0,0,0]
	v_mfma_scale_f32_16x16x128_f8f6f4 v[44:47], v[10:17], v[226:233], v[44:47], v186, v186 op_sel_hi:[0,0,0]
	v_mfma_scale_f32_16x16x128_f8f6f4 v[48:51], v[192:199], v[226:233], v[48:51], v186, v186 op_sel_hi:[0,0,0]
	v_mfma_scale_f32_16x16x128_f8f6f4 v[28:31], v[10:17], v[234:241], v[28:31], v186, v186 op_sel_hi:[0,0,0]
	v_mfma_scale_f32_16x16x128_f8f6f4 v[32:35], v[192:199], v[234:241], v[32:35], v186, v186 op_sel_hi:[0,0,0]
	s_setprio 0
	s_setprio 1
	v_mfma_scale_f32_16x16x128_f8f6f4 v[84:87], v[2:9], v[200:207], v[84:87], v186, v186 op_sel_hi:[0,0,0]
	v_mfma_scale_f32_16x16x128_f8f6f4 v[88:91], v[18:25], v[200:207], v[88:91], v186, v186 op_sel_hi:[0,0,0]
	v_mfma_scale_f32_16x16x128_f8f6f4 v[68:71], v[2:9], v[208:215], v[68:71], v186, v186 op_sel_hi:[0,0,0]
	v_mfma_scale_f32_16x16x128_f8f6f4 v[72:75], v[18:25], v[208:215], v[72:75], v186, v186 op_sel_hi:[0,0,0]
	v_mfma_scale_f32_16x16x128_f8f6f4 v[52:55], v[2:9], v[226:233], v[52:55], v186, v186 op_sel_hi:[0,0,0]
	v_mfma_scale_f32_16x16x128_f8f6f4 v[56:59], v[18:25], v[226:233], v[56:59], v186, v186 op_sel_hi:[0,0,0]
	v_mfma_scale_f32_16x16x128_f8f6f4 v[36:39], v[2:9], v[234:241], v[36:39], v186, v186 op_sel_hi:[0,0,0]
	v_mfma_scale_f32_16x16x128_f8f6f4 v[40:43], v[18:25], v[234:241], v[40:43], v186, v186 op_sel_hi:[0,0,0]
	s_barrier
	s_setprio 0
	s_add_i32 s78, s78, 2
	s_add_u32 s90, s90, 0x100
	s_addc_u32 s91, s91, 0
	s_add_u32 s76, s76, 0x100
	s_addc_u32 s77, s77, 0

.LBB0_211:
	s_lshl_b32 s72, s58, 2
	s_and_b32 s72, s72, 28
	s_ashr_i32 s60, s58, 3
	s_add_i32 s76, s59, s72
	s_ashr_i32 s61, s60, 31
	s_ashr_i32 s77, s76, 31
	s_ashr_i32 s59, s58, 31
	s_lshl_b64 s[60:61], s[60:61], 23
	s_lshl_b64 s[76:77], s[76:77], 16
	s_lshl_b64 s[58:59], s[58:59], 14
	v_mov_b32_e32 v2, v188
	s_add_u32 s58, s57, s58
	s_nop 15
	s_nop 7
	s_addc_u32 s59, s15, s59
	v_lshl_or_b32 v26, v2, 6, v187
	global_load_dwordx4 v[2:5], v26, s[58:59]
	global_load_dwordx4 v[182:185], v26, s[58:59] offset:1024
	global_load_dwordx4 v[22:25], v26, s[58:59] offset:2048
	global_load_dwordx4 v[18:21], v26, s[58:59] offset:3072
	v_and_b32_e32 v7, 64, v224
	v_xor_b32_e32 v6, 16, v224
	v_add_u32_e32 v7, 64, v7
	v_xor_b32_e32 v8, 32, v224
	v_cmp_lt_i32_e32 vcc, v6, v7
	s_waitcnt vmcnt(0)
	v_add_f32_e32 v22, v22, v23
	v_cndmask_b32_e32 v6, v224, v6, vcc
	v_cmp_lt_i32_e32 vcc, v8, v7
	v_add_f32_e32 v2, v2, v3
	v_add_f32_e32 v3, v4, v5
	v_cndmask_b32_e32 v7, v224, v8, vcc
	v_lshlrev_b32_e32 v181, 2, v6
	v_lshlrev_b32_e32 v180, 2, v7
	v_lshl_add_u64 v[6:7], s[58:59], 0, v[26:27]
	v_add_f32_e32 v26, v2, v3
	ds_bpermute_b32 v191, v181, v26
	v_add_co_u32_e32 v178, vcc, s6, v6
	s_add_u32 s58, s50, s60
	s_nop 0
	v_addc_co_u32_e32 v179, vcc, 0, v7, vcc
	s_waitcnt lgkmcnt(0)
	v_add_f32_e32 v26, v26, v191
	global_load_dwordx4 v[14:17], v[178:179], off
	global_load_dwordx4 v[10:13], v[178:179], off offset:1024
	global_load_dwordx4 v[6:9], v[178:179], off offset:2048
	global_load_dwordx4 v[2:5], v[178:179], off offset:3072
	ds_bpermute_b32 v178, v180, v26
	s_addc_u32 s59, s51, s61
	s_add_u32 s40, s58, s40
	s_addc_u32 s41, s59, s41
	s_add_u32 s40, s40, s76
	s_waitcnt lgkmcnt(0)
	v_add_f32_e32 v26, v26, v178
	v_fmamk_f32 v26, v26, 0x3a800000, v222
	v_rsq_f32_e32 v26, v26
	s_addc_u32 s41, s41, s77
	s_add_u32 s40, s40, s46
	s_addc_u32 s41, s41, s47
	v_mul_f32_e32 v26, 0xbcb8aa3b, v26
	v_mul_f32_e32 v148, v148, v26
	v_mul_f32_e32 v152, v152, v26
	v_mul_f32_e32 v149, v149, v26
	v_mul_f32_e32 v153, v153, v26
	v_mul_f32_e32 v140, v140, v26
	v_exp_f32_e32 v148, v148
	v_exp_f32_e32 v152, v152
	v_mul_f32_e32 v150, v150, v26
	v_mul_f32_e32 v154, v154, v26
	v_exp_f32_e32 v149, v149
	v_exp_f32_e32 v153, v153
	v_exp_f32_e32 v140, v140
	v_mul_f32_e32 v151, v151, v26
	v_mul_f32_e32 v155, v155, v26
	v_exp_f32_e32 v150, v150
	v_exp_f32_e32 v154, v154
	v_mul_f32_e32 v141, v141, v26
	v_exp_f32_e32 v151, v151
	v_exp_f32_e32 v155, v155
	v_exp_f32_e32 v141, v141
	v_fmamk_f32 v148, v148, 0x3b808081, v223
	v_fmamk_f32 v152, v152, 0x3b808081, v223
	v_fmamk_f32 v149, v149, 0x3b808081, v223
	v_fmamk_f32 v153, v153, 0x3b808081, v223
	v_fmamk_f32 v140, v140, 0x3b808081, v223
	v_rcp_f32_e32 v148, v148
	v_rcp_f32_e32 v152, v152
	v_fmamk_f32 v150, v150, 0x3b808081, v223
	v_fmamk_f32 v154, v154, 0x3b808081, v223
	v_rcp_f32_e32 v149, v149
	v_rcp_f32_e32 v153, v153
	v_rcp_f32_e32 v140, v140
	v_mul_f32_e32 v144, v144, v26
	v_fmamk_f32 v151, v151, 0x3b808081, v223
	v_fmamk_f32 v155, v155, 0x3b808081, v223
	v_rcp_f32_e32 v150, v150
	v_rcp_f32_e32 v154, v154
	v_exp_f32_e32 v144, v144
	v_fmamk_f32 v141, v141, 0x3b808081, v223
	v_rcp_f32_e32 v151, v151
	v_rcp_f32_e32 v155, v155
	v_rcp_f32_e32 v191, v141
	v_cvt_pk_u8_f32 v141, v148, 0, 0
	v_cvt_pk_u8_f32 v148, v152, 0, 0
	v_cvt_pk_u8_f32 v152, v140, 0, 0
	v_cvt_pk_u8_f32 v140, v149, 1, v141
	v_cvt_pk_u8_f32 v141, v153, 1, v148
	v_cvt_pk_u8_f32 v140, v150, 2, v140
	v_cvt_pk_u8_f32 v141, v154, 2, v141
	v_mul_f32_e32 v145, v145, v26
	v_mul_f32_e32 v142, v142, v26
	v_fmamk_f32 v144, v144, 0x3b808081, v223
	v_cvt_pk_u8_f32 v140, v151, 3, v140
	v_cvt_pk_u8_f32 v141, v155, 3, v141
	v_exp_f32_e32 v145, v145
	v_exp_f32_e32 v142, v142
	v_rcp_f32_e32 v144, v144
	v_add_u32_e32 v148, 0xfefefeff, v140
	v_add_u32_e32 v149, 0xfefefeff, v141
	v_bitop3_b32 v148, v148, v140, v148 bitop3:0x30
	v_bitop3_b32 v149, v149, v141, v149 bitop3:0x30
	v_lshrrev_b32_e32 v148, 7, v148
	v_lshrrev_b32_e32 v149, 7, v149
	v_lshl_add_u64 v[178:179], s[40:41], 0, v[164:165]
	v_and_or_b32 v140, v148, s9, v140
	v_and_or_b32 v141, v149, s9, v141
	v_fmamk_f32 v145, v145, 0x3b808081, v223
	global_store_dwordx2 v[178:179], v[140:141], off
	v_cvt_pk_u8_f32 v140, v144, 0, 0
	v_fmamk_f32 v142, v142, 0x3b808081, v223
	v_mul_f32_e32 v144, v146, v26
	v_rcp_f32_e32 v145, v145
	v_rcp_f32_e32 v142, v142
	v_exp_f32_e32 v144, v144
	v_mul_f32_e32 v143, v143, v26
	v_cvt_pk_u8_f32 v141, v191, 1, v152
	v_exp_f32_e32 v143, v143
	v_cvt_pk_u8_f32 v140, v145, 1, v140
	v_cvt_pk_u8_f32 v141, v142, 2, v141
	v_fmamk_f32 v142, v144, 0x3b808081, v223
	v_add_f32_e32 v144, v182, v183
	v_add_f32_e32 v145, v184, v185
	v_add_f32_e32 v144, v144, v145
	ds_bpermute_b32 v145, v181, v144
	v_rcp_f32_e32 v142, v142
	v_fmamk_f32 v143, v143, 0x3b808081, v223
	v_rcp_f32_e32 v143, v143
	v_mul_f32_e32 v26, v147, v26
	v_cvt_pk_u8_f32 v140, v142, 2, v140
	s_waitcnt lgkmcnt(0)
	v_add_f32_e32 v142, v144, v145
	v_cvt_pk_u8_f32 v141, v143, 3, v141
	ds_bpermute_b32 v143, v180, v142
	v_exp_f32_e32 v26, v26
	v_add_f32_e32 v23, v24, v25
	v_add_f32_e32 v22, v22, v23
	ds_bpermute_b32 v23, v181, v22
	s_waitcnt lgkmcnt(1)
	v_add_f32_e32 v142, v142, v143
	v_fmamk_f32 v26, v26, 0x3b808081, v223
	v_fmamk_f32 v142, v142, 0x3a800000, v222
	v_rcp_f32_e32 v26, v26
	v_rsq_f32_e32 v142, v142
	s_waitcnt lgkmcnt(0)
	v_add_f32_e32 v22, v22, v23
	ds_bpermute_b32 v23, v180, v22
	v_cvt_pk_u8_f32 v26, v26, 3, v140
	v_add_u32_e32 v140, 0xfefefeff, v141
	v_mul_f32_e32 v142, 0xbcb8aa3b, v142
	v_bitop3_b32 v140, v140, v141, v140 bitop3:0x30
	v_mul_f32_e32 v124, v124, v142
	v_lshrrev_b32_e32 v140, 7, v140
	v_exp_f32_e32 v124, v124
	v_mul_f32_e32 v125, v125, v142
	v_and_or_b32 v140, v140, s9, v141
	v_add_u32_e32 v141, 0xfefefeff, v26
	v_exp_f32_e32 v125, v125
	v_bitop3_b32 v141, v141, v26, v141 bitop3:0x30
	v_lshrrev_b32_e32 v141, 7, v141
	v_and_or_b32 v141, v141, s9, v26
	v_fmamk_f32 v26, v124, 0x3b808081, v223
	v_mul_f32_e32 v124, v128, v142
	v_exp_f32_e32 v124, v124
	v_rcp_f32_e32 v26, v26
	v_fmamk_f32 v125, v125, 0x3b808081, v223
	v_mul_f32_e32 v128, v129, v142
	v_rcp_f32_e32 v125, v125
	v_exp_f32_e32 v128, v128
	v_fmamk_f32 v124, v124, 0x3b808081, v223
	v_cvt_pk_u8_f32 v26, v26, 0, 0
	v_rcp_f32_e32 v124, v124
	v_cvt_pk_u8_f32 v26, v125, 1, v26
	v_fmamk_f32 v125, v128, 0x3b808081, v223
	v_mul_f32_e32 v126, v126, v142
	v_mul_f32_e32 v128, v130, v142
	v_rcp_f32_e32 v125, v125
	v_exp_f32_e32 v126, v126
	v_exp_f32_e32 v128, v128
	v_cvt_pk_u8_f32 v124, v124, 0, 0
	v_cvt_pk_u8_f32 v124, v125, 1, v124
	v_fmamk_f32 v125, v126, 0x3b808081, v223
	v_fmamk_f32 v126, v128, 0x3b808081, v223
	v_mul_f32_e32 v127, v127, v142
	v_mul_f32_e32 v128, v131, v142
	v_exp_f32_e32 v127, v127
	v_exp_f32_e32 v128, v128
	v_rcp_f32_e32 v125, v125
	v_rcp_f32_e32 v126, v126
	v_fmamk_f32 v127, v127, 0x3b808081, v223
	v_fmamk_f32 v128, v128, 0x3b808081, v223
	v_rcp_f32_e32 v127, v127
	v_rcp_f32_e32 v128, v128
	v_cvt_pk_u8_f32 v26, v125, 2, v26
	v_cvt_pk_u8_f32 v124, v126, 2, v124
	v_cvt_pk_u8_f32 v26, v127, 3, v26
	v_cvt_pk_u8_f32 v125, v128, 3, v124
	v_add_u32_e32 v124, 0xfefefeff, v26
	v_add_u32_e32 v126, 0xfefefeff, v125
	v_bitop3_b32 v124, v124, v26, v124 bitop3:0x30
	v_bitop3_b32 v126, v126, v125, v126 bitop3:0x30
	v_lshrrev_b32_e32 v124, 7, v124
	v_lshrrev_b32_e32 v126, 7, v126
	v_and_or_b32 v124, v124, s9, v26
	v_mul_f32_e32 v26, v132, v142
	v_mul_f32_e32 v127, v136, v142
	v_and_or_b32 v125, v126, s9, v125
	v_exp_f32_e32 v26, v26
	v_exp_f32_e32 v127, v127
	global_store_dwordx2 v[178:179], v[124:125], off offset:1024
	v_mul_f32_e32 v125, v133, v142
	v_mul_f32_e32 v126, v137, v142
	v_exp_f32_e32 v125, v125
	v_exp_f32_e32 v126, v126
	v_fmamk_f32 v26, v26, 0x3b808081, v223
	v_fmamk_f32 v124, v127, 0x3b808081, v223
	v_rcp_f32_e32 v26, v26
	v_rcp_f32_e32 v124, v124
	v_fmamk_f32 v125, v125, 0x3b808081, v223
	v_fmamk_f32 v126, v126, 0x3b808081, v223
	v_mul_f32_e32 v127, v134, v142
	v_rcp_f32_e32 v125, v125
	v_rcp_f32_e32 v126, v126
	v_exp_f32_e32 v127, v127
	v_cvt_pk_u8_f32 v26, v26, 0, 0
	v_cvt_pk_u8_f32 v124, v124, 0, 0
	v_cvt_pk_u8_f32 v26, v125, 1, v26
	v_cvt_pk_u8_f32 v124, v126, 1, v124
	v_fmamk_f32 v125, v127, 0x3b808081, v223
	v_mul_f32_e32 v126, v138, v142
	v_mul_f32_e32 v127, v135, v142
	v_rcp_f32_e32 v125, v125
	v_exp_f32_e32 v126, v126
	v_exp_f32_e32 v127, v127
	s_waitcnt lgkmcnt(0)
	v_add_f32_e32 v22, v22, v23
	v_cvt_pk_u8_f32 v26, v125, 2, v26
	v_fmamk_f32 v125, v126, 0x3b808081, v223
	v_fmamk_f32 v126, v127, 0x3b808081, v223
	v_mul_f32_e32 v127, v139, v142
	v_exp_f32_e32 v127, v127
	v_rcp_f32_e32 v125, v125
	v_rcp_f32_e32 v126, v126
	v_fmamk_f32 v22, v22, 0x3a800000, v222
	v_fmamk_f32 v25, v127, 0x3b808081, v223
	v_rcp_f32_e32 v25, v25
	v_cvt_pk_u8_f32 v24, v125, 2, v124
	v_cvt_pk_u8_f32 v26, v126, 3, v26
	v_rsq_f32_e32 v23, v22
	v_cvt_pk_u8_f32 v24, v25, 3, v24
	v_add_u32_e32 v25, 0xfefefeff, v26
	v_bitop3_b32 v25, v25, v26, v25 bitop3:0x30
	v_lshrrev_b32_e32 v25, 7, v25
	v_and_or_b32 v22, v25, s9, v26
	v_add_u32_e32 v25, 0xfefefeff, v24
	v_mul_f32_e32 v26, 0xbcb8aa3b, v23
	v_bitop3_b32 v25, v25, v24, v25 bitop3:0x30
	v_mul_f32_e32 v23, v108, v26
	v_exp_f32_e32 v108, v23
	v_lshrrev_b32_e32 v23, 7, v25
	v_and_or_b32 v23, v23, s9, v24
	v_mul_f32_e32 v24, v109, v26
	v_exp_f32_e32 v24, v24
	global_store_dwordx2 v[178:179], v[22:23], off offset:1536
	v_fmamk_f32 v22, v108, 0x3b808081, v223
	v_mul_f32_e32 v23, v112, v26
	v_exp_f32_e32 v23, v23
	v_rcp_f32_e32 v22, v22
	v_fmamk_f32 v24, v24, 0x3b808081, v223
	v_mul_f32_e32 v25, v113, v26
	v_rcp_f32_e32 v24, v24
	v_exp_f32_e32 v25, v25
	v_fmamk_f32 v23, v23, 0x3b808081, v223
	v_cvt_pk_u8_f32 v22, v22, 0, 0
	v_rcp_f32_e32 v23, v23
	v_cvt_pk_u8_f32 v22, v24, 1, v22
	v_fmamk_f32 v24, v25, 0x3b808081, v223
	v_mul_f32_e32 v25, v110, v26
	v_mul_f32_e32 v108, v114, v26
	v_rcp_f32_e32 v24, v24
	v_exp_f32_e32 v25, v25
	v_exp_f32_e32 v108, v108
	v_cvt_pk_u8_f32 v23, v23, 0, 0
	v_cvt_pk_u8_f32 v23, v24, 1, v23
	v_fmamk_f32 v24, v25, 0x3b808081, v223
	v_fmamk_f32 v25, v108, 0x3b808081, v223
	v_mul_f32_e32 v108, v111, v26
	v_exp_f32_e32 v108, v108
	v_rcp_f32_e32 v24, v24
	v_mul_f32_e32 v109, v115, v26
	v_exp_f32_e32 v109, v109
	v_fmamk_f32 v108, v108, 0x3b808081, v223
	v_rcp_f32_e32 v108, v108
	v_cvt_pk_u8_f32 v22, v24, 2, v22
	v_rcp_f32_e32 v25, v25
	v_fmamk_f32 v109, v109, 0x3b808081, v223
	v_cvt_pk_u8_f32 v22, v108, 3, v22
	v_add_u32_e32 v24, 0xfefefeff, v22
	v_bitop3_b32 v24, v24, v22, v24 bitop3:0x30
	v_lshrrev_b32_e32 v24, 7, v24
	v_and_or_b32 v22, v24, s9, v22
	v_mul_f32_e32 v24, v116, v26
	v_rcp_f32_e32 v109, v109
	v_exp_f32_e32 v24, v24
	v_cvt_pk_u8_f32 v23, v25, 2, v23
	v_mul_f32_e32 v108, v120, v26
	v_cvt_pk_u8_f32 v23, v109, 3, v23
	v_fmamk_f32 v24, v24, 0x3b808081, v223
	v_add_u32_e32 v25, 0xfefefeff, v23
	v_rcp_f32_e32 v24, v24
	v_bitop3_b32 v25, v25, v23, v25 bitop3:0x30
	v_lshrrev_b32_e32 v25, 7, v25
	v_and_or_b32 v23, v25, s9, v23
	v_exp_f32_e32 v108, v108
	global_store_dwordx2 v[178:179], v[22:23], off offset:2048
	v_cvt_pk_u8_f32 v22, v24, 0, 0
	v_mul_f32_e32 v24, v117, v26
	v_mul_f32_e32 v25, v121, v26
	v_exp_f32_e32 v24, v24
	v_exp_f32_e32 v25, v25
	v_fmamk_f32 v23, v108, 0x3b808081, v223
	v_rcp_f32_e32 v23, v23
	v_fmamk_f32 v24, v24, 0x3b808081, v223
	v_fmamk_f32 v25, v25, 0x3b808081, v223
	v_mul_f32_e32 v108, v118, v26
	v_add_f32_e32 v18, v18, v19
	v_add_f32_e32 v19, v20, v21
	v_rcp_f32_e32 v24, v24
	v_rcp_f32_e32 v25, v25
	v_exp_f32_e32 v108, v108
	v_add_f32_e32 v18, v18, v19
	ds_bpermute_b32 v19, v181, v18
	v_cvt_pk_u8_f32 v23, v23, 0, 0
	v_cvt_pk_u8_f32 v22, v24, 1, v22
	v_cvt_pk_u8_f32 v23, v25, 1, v23
	v_fmamk_f32 v24, v108, 0x3b808081, v223
	v_mul_f32_e32 v25, v122, v26
	v_mul_f32_e32 v108, v119, v26
	v_rcp_f32_e32 v24, v24
	v_exp_f32_e32 v25, v25
	v_exp_f32_e32 v108, v108
	v_mul_f32_e32 v26, v123, v26
	v_exp_f32_e32 v26, v26
	s_waitcnt lgkmcnt(0)
	v_add_f32_e32 v18, v18, v19
	ds_bpermute_b32 v19, v180, v18
	v_cvt_pk_u8_f32 v22, v24, 2, v22
	v_fmamk_f32 v24, v25, 0x3b808081, v223
	v_fmamk_f32 v25, v108, 0x3b808081, v223
	v_rcp_f32_e32 v24, v24
	v_rcp_f32_e32 v25, v25
	v_fmamk_f32 v21, v26, 0x3b808081, v223
	v_rcp_f32_e32 v21, v21
	s_waitcnt lgkmcnt(0)
	v_add_f32_e32 v18, v18, v19
	v_fmamk_f32 v18, v18, 0x3a800000, v222
	v_cvt_pk_u8_f32 v20, v24, 2, v23
	v_cvt_pk_u8_f32 v22, v25, 3, v22
	v_rsq_f32_e32 v19, v18
	v_cvt_pk_u8_f32 v20, v21, 3, v20
	v_add_u32_e32 v21, 0xfefefeff, v22
	v_bitop3_b32 v21, v21, v22, v21 bitop3:0x30
	v_lshrrev_b32_e32 v21, 7, v21
	v_and_or_b32 v18, v21, s9, v22
	v_add_u32_e32 v21, 0xfefefeff, v20
	v_mul_f32_e32 v22, 0xbcb8aa3b, v19
	v_bitop3_b32 v21, v21, v20, v21 bitop3:0x30
	v_mul_f32_e32 v19, v92, v22
	v_exp_f32_e32 v23, v19
	v_lshrrev_b32_e32 v19, 7, v21
	v_and_or_b32 v19, v19, s9, v20
	v_mul_f32_e32 v20, v93, v22
	v_exp_f32_e32 v20, v20
	global_store_dwordx2 v[178:179], v[18:19], off offset:2560
	v_fmamk_f32 v18, v23, 0x3b808081, v223
	v_mul_f32_e32 v19, v96, v22
	v_exp_f32_e32 v19, v19
	v_rcp_f32_e32 v18, v18
	v_fmamk_f32 v20, v20, 0x3b808081, v223
	v_mul_f32_e32 v21, v97, v22
	v_rcp_f32_e32 v20, v20
	v_exp_f32_e32 v21, v21
	v_fmamk_f32 v19, v19, 0x3b808081, v223
	v_cvt_pk_u8_f32 v18, v18, 0, 0
	v_rcp_f32_e32 v19, v19
	v_cvt_pk_u8_f32 v18, v20, 1, v18
	v_fmamk_f32 v20, v21, 0x3b808081, v223
	v_mul_f32_e32 v21, v94, v22
	v_mul_f32_e32 v23, v98, v22
	v_rcp_f32_e32 v20, v20
	v_exp_f32_e32 v21, v21
	v_exp_f32_e32 v23, v23
	v_cvt_pk_u8_f32 v19, v19, 0, 0
	v_cvt_pk_u8_f32 v19, v20, 1, v19
	v_fmamk_f32 v20, v21, 0x3b808081, v223
	v_fmamk_f32 v21, v23, 0x3b808081, v223
	v_mul_f32_e32 v23, v95, v22
	v_exp_f32_e32 v23, v23
	v_rcp_f32_e32 v20, v20
	v_mul_f32_e32 v24, v99, v22
	v_exp_f32_e32 v24, v24
	v_fmamk_f32 v23, v23, 0x3b808081, v223
	v_rcp_f32_e32 v23, v23
	v_cvt_pk_u8_f32 v18, v20, 2, v18
	v_rcp_f32_e32 v21, v21
	v_fmamk_f32 v24, v24, 0x3b808081, v223
	v_cvt_pk_u8_f32 v18, v23, 3, v18
	v_add_u32_e32 v20, 0xfefefeff, v18
	v_bitop3_b32 v20, v20, v18, v20 bitop3:0x30
	v_lshrrev_b32_e32 v20, 7, v20
	v_and_or_b32 v18, v20, s9, v18
	v_mul_f32_e32 v20, v100, v22
	v_rcp_f32_e32 v24, v24
	v_exp_f32_e32 v20, v20
	v_cvt_pk_u8_f32 v19, v21, 2, v19
	v_mul_f32_e32 v23, v104, v22
	v_cvt_pk_u8_f32 v19, v24, 3, v19
	v_fmamk_f32 v20, v20, 0x3b808081, v223
	v_add_u32_e32 v21, 0xfefefeff, v19
	v_rcp_f32_e32 v20, v20
	v_bitop3_b32 v21, v21, v19, v21 bitop3:0x30
	v_lshrrev_b32_e32 v21, 7, v21
	v_and_or_b32 v19, v21, s9, v19
	v_exp_f32_e32 v23, v23
	global_store_dwordx2 v[178:179], v[18:19], off offset:3072
	v_cvt_pk_u8_f32 v18, v20, 0, 0
	v_mul_f32_e32 v20, v101, v22
	v_mul_f32_e32 v21, v105, v22
	v_exp_f32_e32 v20, v20
	v_exp_f32_e32 v21, v21
	v_fmamk_f32 v19, v23, 0x3b808081, v223
	v_rcp_f32_e32 v19, v19
	v_fmamk_f32 v20, v20, 0x3b808081, v223
	v_fmamk_f32 v21, v21, 0x3b808081, v223
	v_mul_f32_e32 v23, v102, v22
	s_waitcnt vmcnt(9)
	v_add_f32_e32 v14, v14, v15
	v_add_f32_e32 v15, v16, v17
	v_rcp_f32_e32 v20, v20
	v_rcp_f32_e32 v21, v21
	v_exp_f32_e32 v23, v23
	v_add_f32_e32 v14, v14, v15
	ds_bpermute_b32 v15, v181, v14
	v_cvt_pk_u8_f32 v19, v19, 0, 0
	v_cvt_pk_u8_f32 v18, v20, 1, v18
	v_cvt_pk_u8_f32 v19, v21, 1, v19
	v_fmamk_f32 v20, v23, 0x3b808081, v223
	v_mul_f32_e32 v21, v106, v22
	v_mul_f32_e32 v23, v103, v22
	v_rcp_f32_e32 v20, v20
	v_exp_f32_e32 v21, v21
	v_exp_f32_e32 v23, v23
	v_mul_f32_e32 v22, v107, v22
	v_exp_f32_e32 v22, v22
	s_waitcnt lgkmcnt(0)
	v_add_f32_e32 v14, v14, v15
	ds_bpermute_b32 v15, v180, v14
	v_cvt_pk_u8_f32 v18, v20, 2, v18
	v_fmamk_f32 v20, v21, 0x3b808081, v223
	v_fmamk_f32 v21, v23, 0x3b808081, v223
	v_rcp_f32_e32 v20, v20
	v_rcp_f32_e32 v21, v21
	v_fmamk_f32 v17, v22, 0x3b808081, v223
	v_rcp_f32_e32 v17, v17
	s_waitcnt lgkmcnt(0)
	v_add_f32_e32 v14, v14, v15
	v_fmamk_f32 v14, v14, 0x3a800000, v222
	v_cvt_pk_u8_f32 v16, v20, 2, v19
	v_cvt_pk_u8_f32 v18, v21, 3, v18
	v_rsq_f32_e32 v15, v14
	v_cvt_pk_u8_f32 v16, v17, 3, v16
	v_add_u32_e32 v17, 0xfefefeff, v18
	v_bitop3_b32 v17, v17, v18, v17 bitop3:0x30
	v_lshrrev_b32_e32 v17, 7, v17
	v_and_or_b32 v14, v17, s9, v18
	v_add_u32_e32 v17, 0xfefefeff, v16
	v_mul_f32_e32 v18, 0xbcb8aa3b, v15
	v_bitop3_b32 v17, v17, v16, v17 bitop3:0x30
	v_mul_f32_e32 v15, v76, v18
	v_exp_f32_e32 v19, v15
	v_lshrrev_b32_e32 v15, 7, v17
	v_and_or_b32 v15, v15, s9, v16
	v_mul_f32_e32 v16, v77, v18
	v_exp_f32_e32 v16, v16
	global_store_dwordx2 v[178:179], v[14:15], off offset:3584
	v_fmamk_f32 v14, v19, 0x3b808081, v223
	v_mul_f32_e32 v15, v80, v18
	v_exp_f32_e32 v15, v15
	v_rcp_f32_e32 v14, v14
	v_fmamk_f32 v16, v16, 0x3b808081, v223
	v_mul_f32_e32 v17, v81, v18
	v_rcp_f32_e32 v16, v16
	v_exp_f32_e32 v17, v17
	v_fmamk_f32 v15, v15, 0x3b808081, v223
	v_cvt_pk_u8_f32 v14, v14, 0, 0
	v_rcp_f32_e32 v15, v15
	v_cvt_pk_u8_f32 v14, v16, 1, v14
	v_fmamk_f32 v16, v17, 0x3b808081, v223
	v_mul_f32_e32 v17, v78, v18
	v_mul_f32_e32 v19, v82, v18
	v_rcp_f32_e32 v16, v16
	v_exp_f32_e32 v17, v17
	v_exp_f32_e32 v19, v19
	v_cvt_pk_u8_f32 v15, v15, 0, 0
	v_cvt_pk_u8_f32 v15, v16, 1, v15
	v_fmamk_f32 v16, v17, 0x3b808081, v223
	v_fmamk_f32 v17, v19, 0x3b808081, v223
	v_mul_f32_e32 v19, v79, v18
	v_exp_f32_e32 v19, v19
	v_mul_f32_e32 v20, v83, v18
	v_exp_f32_e32 v20, v20
	v_rcp_f32_e32 v16, v16
	v_fmamk_f32 v19, v19, 0x3b808081, v223
	v_rcp_f32_e32 v19, v19
	v_rcp_f32_e32 v17, v17
	v_fmamk_f32 v20, v20, 0x3b808081, v223
	v_rcp_f32_e32 v20, v20
	v_cvt_pk_u8_f32 v14, v16, 2, v14
	v_cvt_pk_u8_f32 v14, v19, 3, v14
	v_add_u32_e32 v16, 0xfefefeff, v14
	v_cvt_pk_u8_f32 v15, v17, 2, v15
	v_bitop3_b32 v16, v16, v14, v16 bitop3:0x30
	v_mul_f32_e32 v17, v84, v18
	v_cvt_pk_u8_f32 v15, v20, 3, v15
	v_lshrrev_b32_e32 v16, 7, v16
	v_exp_f32_e32 v19, v17
	v_and_or_b32 v16, v16, s9, v14
	v_add_u32_e32 v14, 0xfefefeff, v15
	v_bitop3_b32 v14, v14, v15, v14 bitop3:0x30
	v_lshrrev_b32_e32 v14, 7, v14
	v_and_or_b32 v17, v14, s9, v15
	v_fmamk_f32 v14, v19, 0x3b808081, v223
	v_rcp_f32_e32 v19, v14
	v_mul_f32_e32 v14, v88, v18
	v_exp_f32_e32 v20, v14
	v_add_co_u32_e32 v14, vcc, s10, v178
	v_mul_f32_e32 v21, v86, v18
	s_nop 0
	v_addc_co_u32_e32 v15, vcc, 0, v179, vcc
	global_store_dwordx2 v[14:15], v[16:17], off
	v_cvt_pk_u8_f32 v16, v19, 0, 0
	v_fmamk_f32 v17, v20, 0x3b808081, v223
	v_mul_f32_e32 v19, v85, v18
	v_mul_f32_e32 v20, v89, v18
	v_exp_f32_e32 v19, v19
	v_exp_f32_e32 v20, v20
	v_rcp_f32_e32 v17, v17
	s_waitcnt vmcnt(10)
	v_add_f32_e32 v10, v10, v11
	v_fmamk_f32 v19, v19, 0x3b808081, v223
	v_fmamk_f32 v20, v20, 0x3b808081, v223
	v_add_f32_e32 v11, v12, v13
	v_rcp_f32_e32 v19, v19
	v_rcp_f32_e32 v20, v20
	v_exp_f32_e32 v21, v21
	v_add_f32_e32 v10, v10, v11
	ds_bpermute_b32 v11, v181, v10
	v_cvt_pk_u8_f32 v17, v17, 0, 0
	v_cvt_pk_u8_f32 v16, v19, 1, v16
	v_cvt_pk_u8_f32 v17, v20, 1, v17
	v_fmamk_f32 v19, v21, 0x3b808081, v223
	v_mul_f32_e32 v20, v90, v18
	v_mul_f32_e32 v21, v87, v18
	v_rcp_f32_e32 v19, v19
	v_exp_f32_e32 v20, v20
	v_exp_f32_e32 v21, v21
	v_mul_f32_e32 v18, v91, v18
	v_exp_f32_e32 v18, v18
	s_waitcnt lgkmcnt(0)
	v_add_f32_e32 v10, v10, v11
	ds_bpermute_b32 v11, v180, v10
	v_cvt_pk_u8_f32 v16, v19, 2, v16
	v_fmamk_f32 v19, v20, 0x3b808081, v223
	v_fmamk_f32 v20, v21, 0x3b808081, v223
	v_rcp_f32_e32 v19, v19
	v_rcp_f32_e32 v20, v20
	v_fmamk_f32 v13, v18, 0x3b808081, v223
	v_rcp_f32_e32 v13, v13
	s_waitcnt lgkmcnt(0)
	v_add_f32_e32 v10, v10, v11
	v_fmamk_f32 v10, v10, 0x3a800000, v222
	v_cvt_pk_u8_f32 v12, v19, 2, v17
	v_cvt_pk_u8_f32 v16, v20, 3, v16
	v_rsq_f32_e32 v11, v10
	v_cvt_pk_u8_f32 v12, v13, 3, v12
	v_add_u32_e32 v13, 0xfefefeff, v16
	v_bitop3_b32 v13, v13, v16, v13 bitop3:0x30
	v_lshrrev_b32_e32 v13, 7, v13
	v_and_or_b32 v10, v13, s9, v16
	v_add_u32_e32 v13, 0xfefefeff, v12
	v_mul_f32_e32 v16, 0xbcb8aa3b, v11
	v_bitop3_b32 v13, v13, v12, v13 bitop3:0x30
	v_mul_f32_e32 v11, v60, v16
	v_exp_f32_e32 v17, v11
	v_lshrrev_b32_e32 v11, 7, v13
	v_and_or_b32 v11, v11, s9, v12
	v_mul_f32_e32 v12, v61, v16
	v_exp_f32_e32 v12, v12
	global_store_dwordx2 v[14:15], v[10:11], off offset:512
	v_fmamk_f32 v10, v17, 0x3b808081, v223
	v_mul_f32_e32 v11, v64, v16
	v_exp_f32_e32 v11, v11
	v_rcp_f32_e32 v10, v10
	v_fmamk_f32 v12, v12, 0x3b808081, v223
	v_mul_f32_e32 v13, v65, v16
	v_rcp_f32_e32 v12, v12
	v_exp_f32_e32 v13, v13
	v_fmamk_f32 v11, v11, 0x3b808081, v223
	v_cvt_pk_u8_f32 v10, v10, 0, 0
	v_rcp_f32_e32 v11, v11
	v_cvt_pk_u8_f32 v10, v12, 1, v10
	v_fmamk_f32 v12, v13, 0x3b808081, v223
	v_mul_f32_e32 v13, v62, v16
	v_mul_f32_e32 v17, v66, v16
	v_rcp_f32_e32 v12, v12
	v_exp_f32_e32 v13, v13
	v_exp_f32_e32 v17, v17
	v_cvt_pk_u8_f32 v11, v11, 0, 0
	v_cvt_pk_u8_f32 v11, v12, 1, v11
	v_fmamk_f32 v12, v13, 0x3b808081, v223
	v_fmamk_f32 v13, v17, 0x3b808081, v223
	v_mul_f32_e32 v17, v63, v16
	v_exp_f32_e32 v17, v17
	v_rcp_f32_e32 v12, v12
	v_mul_f32_e32 v18, v67, v16
	v_exp_f32_e32 v18, v18
	v_fmamk_f32 v17, v17, 0x3b808081, v223
	v_rcp_f32_e32 v17, v17
	v_cvt_pk_u8_f32 v10, v12, 2, v10
	v_rcp_f32_e32 v13, v13
	v_fmamk_f32 v18, v18, 0x3b808081, v223
	v_cvt_pk_u8_f32 v10, v17, 3, v10
	v_add_u32_e32 v12, 0xfefefeff, v10
	v_bitop3_b32 v12, v12, v10, v12 bitop3:0x30
	v_lshrrev_b32_e32 v12, 7, v12
	v_and_or_b32 v10, v12, s9, v10
	v_mul_f32_e32 v12, v68, v16
	v_rcp_f32_e32 v18, v18
	v_exp_f32_e32 v12, v12
	v_cvt_pk_u8_f32 v11, v13, 2, v11
	v_mul_f32_e32 v17, v72, v16
	v_cvt_pk_u8_f32 v11, v18, 3, v11
	v_fmamk_f32 v12, v12, 0x3b808081, v223
	v_add_u32_e32 v13, 0xfefefeff, v11
	v_rcp_f32_e32 v12, v12
	v_bitop3_b32 v13, v13, v11, v13 bitop3:0x30
	v_lshrrev_b32_e32 v13, 7, v13
	v_and_or_b32 v11, v13, s9, v11
	v_exp_f32_e32 v17, v17
	global_store_dwordx2 v[14:15], v[10:11], off offset:1024
	v_cvt_pk_u8_f32 v10, v12, 0, 0
	v_mul_f32_e32 v12, v69, v16
	v_mul_f32_e32 v13, v73, v16
	v_exp_f32_e32 v12, v12
	v_exp_f32_e32 v13, v13
	v_fmamk_f32 v11, v17, 0x3b808081, v223
	v_rcp_f32_e32 v11, v11
	v_fmamk_f32 v12, v12, 0x3b808081, v223
	v_fmamk_f32 v13, v13, 0x3b808081, v223
	v_mul_f32_e32 v17, v70, v16
	s_waitcnt vmcnt(11)
	v_add_f32_e32 v6, v6, v7
	v_add_f32_e32 v7, v8, v9
	v_rcp_f32_e32 v12, v12
	v_rcp_f32_e32 v13, v13
	v_exp_f32_e32 v17, v17
	v_add_f32_e32 v6, v6, v7
	ds_bpermute_b32 v7, v181, v6
	v_cvt_pk_u8_f32 v11, v11, 0, 0
	v_cvt_pk_u8_f32 v10, v12, 1, v10
	v_cvt_pk_u8_f32 v11, v13, 1, v11
	v_fmamk_f32 v12, v17, 0x3b808081, v223
	v_mul_f32_e32 v13, v74, v16
	v_mul_f32_e32 v17, v71, v16
	v_rcp_f32_e32 v12, v12
	v_exp_f32_e32 v13, v13
	v_exp_f32_e32 v17, v17
	v_mul_f32_e32 v16, v75, v16
	v_exp_f32_e32 v16, v16
	s_waitcnt lgkmcnt(0)
	v_add_f32_e32 v6, v6, v7
	ds_bpermute_b32 v7, v180, v6
	v_cvt_pk_u8_f32 v10, v12, 2, v10
	v_fmamk_f32 v12, v13, 0x3b808081, v223
	v_fmamk_f32 v13, v17, 0x3b808081, v223
	v_rcp_f32_e32 v12, v12
	v_rcp_f32_e32 v13, v13
	v_fmamk_f32 v9, v16, 0x3b808081, v223
	v_rcp_f32_e32 v9, v9
	s_waitcnt lgkmcnt(0)
	v_add_f32_e32 v6, v6, v7
	v_fmamk_f32 v6, v6, 0x3a800000, v222
	v_cvt_pk_u8_f32 v8, v12, 2, v11
	v_cvt_pk_u8_f32 v10, v13, 3, v10
	v_rsq_f32_e32 v7, v6
	v_cvt_pk_u8_f32 v8, v9, 3, v8
	v_add_u32_e32 v9, 0xfefefeff, v10
	v_bitop3_b32 v9, v9, v10, v9 bitop3:0x30
	v_lshrrev_b32_e32 v9, 7, v9
	v_and_or_b32 v6, v9, s9, v10
	v_add_u32_e32 v9, 0xfefefeff, v8
	v_mul_f32_e32 v10, 0xbcb8aa3b, v7
	v_bitop3_b32 v9, v9, v8, v9 bitop3:0x30
	v_mul_f32_e32 v7, v44, v10
	v_exp_f32_e32 v11, v7
	v_lshrrev_b32_e32 v7, 7, v9
	v_and_or_b32 v7, v7, s9, v8
	v_mul_f32_e32 v8, v45, v10
	v_exp_f32_e32 v8, v8
	global_store_dwordx2 v[14:15], v[6:7], off offset:1536
	v_fmamk_f32 v6, v11, 0x3b808081, v223
	v_mul_f32_e32 v7, v48, v10
	v_exp_f32_e32 v7, v7
	v_rcp_f32_e32 v6, v6
	v_fmamk_f32 v8, v8, 0x3b808081, v223
	v_mul_f32_e32 v9, v49, v10
	v_rcp_f32_e32 v8, v8
	v_exp_f32_e32 v9, v9
	v_fmamk_f32 v7, v7, 0x3b808081, v223
	v_cvt_pk_u8_f32 v6, v6, 0, 0
	v_rcp_f32_e32 v7, v7
	v_cvt_pk_u8_f32 v6, v8, 1, v6
	v_fmamk_f32 v8, v9, 0x3b808081, v223
	v_mul_f32_e32 v9, v46, v10
	v_mul_f32_e32 v11, v50, v10
	v_rcp_f32_e32 v8, v8
	v_exp_f32_e32 v9, v9
	v_exp_f32_e32 v11, v11
	v_cvt_pk_u8_f32 v7, v7, 0, 0
	v_cvt_pk_u8_f32 v7, v8, 1, v7
	v_fmamk_f32 v8, v9, 0x3b808081, v223
	v_fmamk_f32 v9, v11, 0x3b808081, v223
	v_mul_f32_e32 v11, v47, v10
	v_exp_f32_e32 v11, v11
	v_rcp_f32_e32 v8, v8
	v_mul_f32_e32 v12, v51, v10
	v_exp_f32_e32 v12, v12
	v_fmamk_f32 v11, v11, 0x3b808081, v223
	v_rcp_f32_e32 v11, v11
	v_cvt_pk_u8_f32 v6, v8, 2, v6
	v_rcp_f32_e32 v9, v9
	v_fmamk_f32 v12, v12, 0x3b808081, v223
	v_cvt_pk_u8_f32 v6, v11, 3, v6
	v_add_u32_e32 v8, 0xfefefeff, v6
	v_bitop3_b32 v8, v8, v6, v8 bitop3:0x30
	v_lshrrev_b32_e32 v8, 7, v8
	v_and_or_b32 v6, v8, s9, v6
	v_mul_f32_e32 v8, v52, v10
	v_rcp_f32_e32 v12, v12
	v_exp_f32_e32 v8, v8
	v_cvt_pk_u8_f32 v7, v9, 2, v7
	v_mul_f32_e32 v11, v56, v10
	v_cvt_pk_u8_f32 v7, v12, 3, v7
	v_fmamk_f32 v8, v8, 0x3b808081, v223
	v_add_u32_e32 v9, 0xfefefeff, v7
	v_rcp_f32_e32 v8, v8
	v_bitop3_b32 v9, v9, v7, v9 bitop3:0x30
	v_lshrrev_b32_e32 v9, 7, v9
	v_and_or_b32 v7, v9, s9, v7
	v_exp_f32_e32 v11, v11
	global_store_dwordx2 v[14:15], v[6:7], off offset:2048
	v_cvt_pk_u8_f32 v6, v8, 0, 0
	v_mul_f32_e32 v8, v53, v10
	v_mul_f32_e32 v9, v57, v10
	v_exp_f32_e32 v8, v8
	v_exp_f32_e32 v9, v9
	v_fmamk_f32 v7, v11, 0x3b808081, v223
	v_rcp_f32_e32 v7, v7
	v_fmamk_f32 v8, v8, 0x3b808081, v223
	v_fmamk_f32 v9, v9, 0x3b808081, v223
	v_mul_f32_e32 v11, v54, v10
	s_waitcnt vmcnt(12)
	v_add_f32_e32 v2, v2, v3
	v_add_f32_e32 v3, v4, v5
	v_rcp_f32_e32 v8, v8
	v_rcp_f32_e32 v9, v9
	v_exp_f32_e32 v11, v11
	v_add_f32_e32 v2, v2, v3
	ds_bpermute_b32 v3, v181, v2
	v_cvt_pk_u8_f32 v7, v7, 0, 0
	v_cvt_pk_u8_f32 v6, v8, 1, v6
	v_cvt_pk_u8_f32 v7, v9, 1, v7
	v_fmamk_f32 v8, v11, 0x3b808081, v223
	v_mul_f32_e32 v9, v58, v10
	v_mul_f32_e32 v11, v55, v10
	v_rcp_f32_e32 v8, v8
	v_exp_f32_e32 v9, v9
	v_exp_f32_e32 v11, v11
	v_mul_f32_e32 v10, v59, v10
	v_exp_f32_e32 v10, v10
	s_waitcnt lgkmcnt(0)
	v_add_f32_e32 v2, v2, v3
	ds_bpermute_b32 v3, v180, v2
	v_cvt_pk_u8_f32 v6, v8, 2, v6
	v_fmamk_f32 v8, v9, 0x3b808081, v223
	v_fmamk_f32 v9, v11, 0x3b808081, v223
	v_rcp_f32_e32 v8, v8
	v_rcp_f32_e32 v9, v9
	v_fmamk_f32 v5, v10, 0x3b808081, v223
	v_rcp_f32_e32 v5, v5
	s_waitcnt lgkmcnt(0)
	v_add_f32_e32 v2, v2, v3
	v_fmamk_f32 v2, v2, 0x3a800000, v222
	v_cvt_pk_u8_f32 v4, v8, 2, v7
	v_cvt_pk_u8_f32 v6, v9, 3, v6
	v_rsq_f32_e32 v3, v2
	v_cvt_pk_u8_f32 v4, v5, 3, v4
	v_add_u32_e32 v5, 0xfefefeff, v6
	v_bitop3_b32 v5, v5, v6, v5 bitop3:0x30
	v_lshrrev_b32_e32 v5, 7, v5
	v_and_or_b32 v2, v5, s9, v6
	v_add_u32_e32 v5, 0xfefefeff, v4
	v_mul_f32_e32 v6, 0xbcb8aa3b, v3
	v_bitop3_b32 v5, v5, v4, v5 bitop3:0x30
	v_mul_f32_e32 v3, v28, v6
	v_exp_f32_e32 v7, v3
	v_lshrrev_b32_e32 v3, 7, v5
	v_and_or_b32 v3, v3, s9, v4
	v_mul_f32_e32 v4, v29, v6
	v_exp_f32_e32 v4, v4
	global_store_dwordx2 v[14:15], v[2:3], off offset:2560
	v_fmamk_f32 v2, v7, 0x3b808081, v223
	v_mul_f32_e32 v3, v32, v6
	v_exp_f32_e32 v3, v3
	v_rcp_f32_e32 v2, v2
	v_fmamk_f32 v4, v4, 0x3b808081, v223
	v_mul_f32_e32 v5, v33, v6
	v_rcp_f32_e32 v4, v4
	v_exp_f32_e32 v5, v5
	v_fmamk_f32 v3, v3, 0x3b808081, v223
	v_cvt_pk_u8_f32 v2, v2, 0, 0
	v_rcp_f32_e32 v3, v3
	v_cvt_pk_u8_f32 v2, v4, 1, v2
	v_fmamk_f32 v4, v5, 0x3b808081, v223
	v_mul_f32_e32 v5, v30, v6
	v_mul_f32_e32 v7, v34, v6
	v_rcp_f32_e32 v4, v4
	v_exp_f32_e32 v5, v5
	v_exp_f32_e32 v7, v7
	v_cvt_pk_u8_f32 v3, v3, 0, 0
	v_cvt_pk_u8_f32 v3, v4, 1, v3
	v_fmamk_f32 v4, v5, 0x3b808081, v223
	v_fmamk_f32 v5, v7, 0x3b808081, v223
	v_mul_f32_e32 v7, v31, v6
	v_exp_f32_e32 v7, v7
	v_mul_f32_e32 v8, v35, v6
	v_exp_f32_e32 v8, v8
	v_rcp_f32_e32 v4, v4
	v_fmamk_f32 v7, v7, 0x3b808081, v223
	v_rcp_f32_e32 v7, v7
	v_rcp_f32_e32 v5, v5
	v_fmamk_f32 v8, v8, 0x3b808081, v223
	v_rcp_f32_e32 v8, v8
	v_cvt_pk_u8_f32 v2, v4, 2, v2
	v_cvt_pk_u8_f32 v2, v7, 3, v2
	v_add_u32_e32 v4, 0xfefefeff, v2
	v_cvt_pk_u8_f32 v3, v5, 2, v3
	v_bitop3_b32 v4, v4, v2, v4 bitop3:0x30
	v_cvt_pk_u8_f32 v3, v8, 3, v3
	v_lshrrev_b32_e32 v4, 7, v4
	v_and_or_b32 v2, v4, s9, v2
	v_add_u32_e32 v4, 0xfefefeff, v3
	v_bitop3_b32 v4, v4, v3, v4 bitop3:0x30
	v_mul_f32_e32 v5, v36, v6
	v_lshrrev_b32_e32 v4, 7, v4
	v_exp_f32_e32 v5, v5
	v_and_or_b32 v3, v4, s9, v3
	v_mul_f32_e32 v4, v37, v6
	v_exp_f32_e32 v4, v4
	global_store_dwordx2 v[14:15], v[2:3], off offset:3072
	v_fmamk_f32 v2, v5, 0x3b808081, v223
	v_mul_f32_e32 v3, v40, v6
	v_exp_f32_e32 v3, v3
	v_rcp_f32_e32 v2, v2
	v_fmamk_f32 v4, v4, 0x3b808081, v223
	v_mul_f32_e32 v5, v41, v6
	v_rcp_f32_e32 v4, v4
	v_exp_f32_e32 v5, v5
	v_fmamk_f32 v3, v3, 0x3b808081, v223
	v_cvt_pk_u8_f32 v2, v2, 0, 0
	v_rcp_f32_e32 v3, v3
	v_cvt_pk_u8_f32 v2, v4, 1, v2
	v_fmamk_f32 v4, v5, 0x3b808081, v223
	v_mul_f32_e32 v5, v38, v6
	v_mul_f32_e32 v7, v42, v6
	v_rcp_f32_e32 v4, v4
	v_exp_f32_e32 v5, v5
	v_exp_f32_e32 v7, v7
	v_cvt_pk_u8_f32 v3, v3, 0, 0
	v_cvt_pk_u8_f32 v3, v4, 1, v3
	v_fmamk_f32 v4, v5, 0x3b808081, v223
	v_fmamk_f32 v5, v7, 0x3b808081, v223
	v_mul_f32_e32 v7, v39, v6
	v_exp_f32_e32 v7, v7
	v_mul_f32_e32 v6, v43, v6
	v_exp_f32_e32 v6, v6
	v_rcp_f32_e32 v4, v4
	v_fmamk_f32 v7, v7, 0x3b808081, v223
	v_rcp_f32_e32 v7, v7
	v_rcp_f32_e32 v5, v5
	v_fmamk_f32 v6, v6, 0x3b808081, v223
	v_rcp_f32_e32 v6, v6
	v_cvt_pk_u8_f32 v2, v4, 2, v2
	v_cvt_pk_u8_f32 v2, v7, 3, v2
	v_add_u32_e32 v4, 0xfefefeff, v2
	v_cvt_pk_u8_f32 v3, v5, 2, v3
	v_bitop3_b32 v4, v4, v2, v4 bitop3:0x30
	v_cvt_pk_u8_f32 v3, v6, 3, v3
	v_lshrrev_b32_e32 v4, 7, v4
	v_and_or_b32 v2, v4, s9, v2
	v_add_u32_e32 v4, 0xfefefeff, v3
	v_bitop3_b32 v4, v4, v3, v4 bitop3:0x30
	v_lshrrev_b32_e32 v4, 7, v4
	v_and_or_b32 v3, v4, s9, v3
	v_mov_b32_e32 v26, v27
	global_store_dwordx2 v[14:15], v[2:3], off offset:3584
	v_mov_b32_e32 v28, v27
	v_mov_b32_e32 v29, v27
	v_mov_b64_e32 v[2:3], v[26:27]
	v_mov_b64_e32 v[4:5], v[28:29]
	global_store_dwordx2 v[178:179], v[140:141], off offset:512
	s_mov_b64 s[60:61], -1
	s_andn2_b64 vcc, exec, s[38:39]
	s_mov_b64 s[38:39], -1
	s_cbranch_vccnz .LBB0_204
	s_andn2_b64 vcc, exec, s[0:1]
	s_cbranch_vccnz .LBB0_203
	s_barrier
	s_branch .LBB0_203

.LBB0_382:
	s_add_u32 s52, s52, 0x20080
	s_addc_u32 s53, s53, 0
	s_add_u32 s35, s20, 0x100
	s_addc_u32 s47, s21, 0
	s_mov_b32 s68, -2
	s_add_u32 s12, s52, 0xfffe0080
	s_addc_u32 s54, s53, -1
	s_add_i32 s72, 0, 0x10000
	s_cmp_eq_u32 s68, 4
	s_cselect_b32 s59, s37, s54
	s_cselect_b32 s58, s36, s12
	s_cselect_b32 s55, s21, s47
	s_cselect_b32 s54, s20, s35
	s_add_i32 s12, 0, 0x14000
	v_add_u32_e32 v14, s72, v190
	v_add_u32_e32 v26, s12, v190
	ds_read_b128 v[2:5], v14
	ds_read_b128 v[6:9], v14 offset:1024
	ds_read_b128 v[10:13], v14 offset:2048
	ds_read_b128 v[14:17], v14 offset:3072
	ds_read_b128 v[18:21], v26
	ds_read_b128 v[22:25], v26 offset:1024
	ds_read_b128 v[192:195], v26 offset:2048
	ds_read_b128 v[196:199], v26 offset:3072
	v_lshl_add_u64 v[216:217], s[52:53], 0, v[166:167]
	s_add_i32 m0, s11, 0xc000
	ds_read_b128 v[178:181], v191
	ds_read_b128 v[182:185], v191 offset:1024
	ds_read_b128 v[200:203], v191 offset:2048
	ds_read_b128 v[204:207], v191 offset:3072
	ds_read_b128 v[208:211], v191 offset:4096
	ds_read_b128 v[212:215], v191 offset:5120
	ds_read_b128 v[226:229], v191 offset:6144
	ds_read_b128 v[230:233], v191 offset:7168
	global_load_lds_dwordx4 v[216:217], off
	v_lshl_add_u64 v[216:217], s[52:53], 0, v[176:177]
	s_add_i32 m0, s11, 0xe000
	s_nop 0
	global_load_lds_dwordx4 v[216:217], off
	s_waitcnt vmcnt(8)
	s_waitcnt lgkmcnt(0)
	s_setprio 1
	s_barrier
	v_mfma_scale_f32_16x16x128_f8f6f4 v[140:143], v[2:9], v[178:185], 0, v187, v187 op_sel_hi:[0,0,0]
	v_mfma_scale_f32_16x16x128_f8f6f4 v[144:147], v[10:17], v[178:185], 0, v187, v187 op_sel_hi:[0,0,0]
	v_mfma_scale_f32_16x16x128_f8f6f4 v[124:127], v[2:9], v[200:207], 0, v187, v187 op_sel_hi:[0,0,0]
	v_mfma_scale_f32_16x16x128_f8f6f4 v[128:131], v[10:17], v[200:207], 0, v187, v187 op_sel_hi:[0,0,0]
	v_mfma_scale_f32_16x16x128_f8f6f4 v[108:111], v[2:9], v[208:215], 0, v187, v187 op_sel_hi:[0,0,0]
	v_mfma_scale_f32_16x16x128_f8f6f4 v[112:115], v[10:17], v[208:215], 0, v187, v187 op_sel_hi:[0,0,0]
	v_mfma_scale_f32_16x16x128_f8f6f4 v[76:79], v[2:9], v[226:233], 0, v187, v187 op_sel_hi:[0,0,0]
	v_mfma_scale_f32_16x16x128_f8f6f4 v[84:87], v[10:17], v[226:233], 0, v187, v187 op_sel_hi:[0,0,0]
	s_setprio 0
	s_setprio 1
	v_mfma_scale_f32_16x16x128_f8f6f4 v[148:151], v[18:25], v[178:185], 0, v187, v187 op_sel_hi:[0,0,0]
	v_mfma_scale_f32_16x16x128_f8f6f4 v[152:155], v[192:199], v[178:185], 0, v187, v187 op_sel_hi:[0,0,0]
	v_mfma_scale_f32_16x16x128_f8f6f4 v[132:135], v[18:25], v[200:207], 0, v187, v187 op_sel_hi:[0,0,0]
	v_mfma_scale_f32_16x16x128_f8f6f4 v[136:139], v[192:199], v[200:207], 0, v187, v187 op_sel_hi:[0,0,0]
	v_mfma_scale_f32_16x16x128_f8f6f4 v[116:119], v[18:25], v[208:215], 0, v187, v187 op_sel_hi:[0,0,0]
	v_mfma_scale_f32_16x16x128_f8f6f4 v[120:123], v[192:199], v[208:215], 0, v187, v187 op_sel_hi:[0,0,0]
	v_mfma_scale_f32_16x16x128_f8f6f4 v[96:99], v[18:25], v[226:233], 0, v187, v187 op_sel_hi:[0,0,0]
	v_mfma_scale_f32_16x16x128_f8f6f4 v[104:107], v[192:199], v[226:233], 0, v187, v187 op_sel_hi:[0,0,0]
	s_barrier
	s_setprio 0
	s_add_i32 s72, s72, s8
	v_lshl_add_u64 v[178:179], s[54:55], 0, v[158:159]
	s_mov_b32 m0, s72
	ds_read_b128 v[200:203], v191 offset:16384
	ds_read_b128 v[204:207], v191 offset:17408
	ds_read_b128 v[208:211], v191 offset:18432
	ds_read_b128 v[212:215], v191 offset:19456
	ds_read_b128 v[226:229], v191 offset:20480
	ds_read_b128 v[230:233], v191 offset:21504
	ds_read_b128 v[234:237], v191 offset:22528
	ds_read_b128 v[238:241], v191 offset:23552
	global_load_lds_dwordx4 v[178:179], off
	s_add_i32 m0, s72, 0x2000
	s_add_u32 s72, s54, 0x20000
	v_lshl_add_u64 v[180:181], s[54:55], 0, v[162:163]
	s_addc_u32 s73, s55, 0
	s_add_i32 s12, s12, s8
	global_load_lds_dwordx4 v[180:181], off
	v_lshl_add_u64 v[182:183], s[72:73], 0, v[158:159]
	s_mov_b32 m0, s12
	v_lshl_add_u64 v[184:185], s[58:59], 0, v[160:161]
	global_load_lds_dwordx4 v[182:183], off
	v_lshl_add_u64 v[182:183], s[72:73], 0, v[162:163]
	s_add_i32 m0, s12, 0x2000
	s_nop 0
	global_load_lds_dwordx4 v[182:183], off
	v_lshl_add_u64 v[182:183], s[58:59], 0, v[156:157]
	s_mov_b32 m0, s11
	s_nop 0
	global_load_lds_dwordx4 v[182:183], off
	s_mov_b32 m0, s16
	s_nop 0
	global_load_lds_dwordx4 v[184:185], off
	s_waitcnt vmcnt(8)
	s_waitcnt lgkmcnt(0)
	s_setprio 1
	s_barrier
	v_mfma_scale_f32_16x16x128_f8f6f4 v[80:83], v[2:9], v[200:207], 0, v187, v187 op_sel_hi:[0,0,0]
	v_mfma_scale_f32_16x16x128_f8f6f4 v[88:91], v[10:17], v[200:207], 0, v187, v187 op_sel_hi:[0,0,0]
	v_mfma_scale_f32_16x16x128_f8f6f4 v[60:63], v[2:9], v[208:215], 0, v187, v187 op_sel_hi:[0,0,0]
	v_mfma_scale_f32_16x16x128_f8f6f4 v[64:67], v[10:17], v[208:215], 0, v187, v187 op_sel_hi:[0,0,0]
	v_mfma_scale_f32_16x16x128_f8f6f4 v[44:47], v[2:9], v[226:233], 0, v187, v187 op_sel_hi:[0,0,0]
	v_mfma_scale_f32_16x16x128_f8f6f4 v[48:51], v[10:17], v[226:233], 0, v187, v187 op_sel_hi:[0,0,0]
	v_mfma_scale_f32_16x16x128_f8f6f4 v[28:31], v[2:9], v[234:241], 0, v187, v187 op_sel_hi:[0,0,0]
	v_mfma_scale_f32_16x16x128_f8f6f4 v[32:35], v[10:17], v[234:241], 0, v187, v187 op_sel_hi:[0,0,0]
	s_setprio 0
	s_setprio 1
	v_mfma_scale_f32_16x16x128_f8f6f4 v[92:95], v[18:25], v[200:207], 0, v187, v187 op_sel_hi:[0,0,0]
	v_mfma_scale_f32_16x16x128_f8f6f4 v[100:103], v[192:199], v[200:207], 0, v187, v187 op_sel_hi:[0,0,0]
	v_mfma_scale_f32_16x16x128_f8f6f4 v[68:71], v[18:25], v[208:215], 0, v187, v187 op_sel_hi:[0,0,0]
	v_mfma_scale_f32_16x16x128_f8f6f4 v[72:75], v[192:199], v[208:215], 0, v187, v187 op_sel_hi:[0,0,0]
	v_mfma_scale_f32_16x16x128_f8f6f4 v[52:55], v[18:25], v[226:233], 0, v187, v187 op_sel_hi:[0,0,0]
	v_mfma_scale_f32_16x16x128_f8f6f4 v[56:59], v[192:199], v[226:233], 0, v187, v187 op_sel_hi:[0,0,0]
	v_mfma_scale_f32_16x16x128_f8f6f4 v[36:39], v[18:25], v[234:241], 0, v187, v187 op_sel_hi:[0,0,0]
	v_mfma_scale_f32_16x16x128_f8f6f4 v[40:43], v[192:199], v[234:241], 0, v187, v187 op_sel_hi:[0,0,0]
	s_barrier
	s_setprio 0
	s_add_i32 s74, 0, 0x18000
	s_add_i32 s12, 0, 0x1c000
	v_add_u32_e32 v2, s74, v190
	v_add_u32_e32 v22, s12, v190
	ds_read_b128 v[10:13], v2
	ds_read_b128 v[14:17], v2 offset:1024
	ds_read_b128 v[192:195], v2 offset:2048
	ds_read_b128 v[196:199], v2 offset:3072
	ds_read_b128 v[2:5], v22
	ds_read_b128 v[6:9], v22 offset:1024
	ds_read_b128 v[18:21], v22 offset:2048
	ds_read_b128 v[22:25], v22 offset:3072
	s_add_u32 s58, s58, 0x20000
	s_addc_u32 s59, s59, 0
	s_mov_b32 m0, s17
	v_lshl_add_u64 v[216:217], s[58:59], 0, v[156:157]
	ds_read_b128 v[200:203], v191 offset:32768
	ds_read_b128 v[204:207], v191 offset:33792
	ds_read_b128 v[208:211], v191 offset:34816
	ds_read_b128 v[212:215], v191 offset:35840
	ds_read_b128 v[226:229], v191 offset:36864
	ds_read_b128 v[230:233], v191 offset:37888
	ds_read_b128 v[234:237], v191 offset:38912
	ds_read_b128 v[238:241], v191 offset:39936
	global_load_lds_dwordx4 v[216:217], off
	v_lshl_add_u64 v[216:217], s[58:59], 0, v[160:161]
	s_mov_b32 m0, s22
	s_nop 0
	global_load_lds_dwordx4 v[216:217], off
	s_waitcnt vmcnt(8)
	s_waitcnt lgkmcnt(0)
	s_setprio 1
	s_barrier
	v_mfma_scale_f32_16x16x128_f8f6f4 v[140:143], v[10:17], v[200:207], v[140:143], v187, v187 op_sel_hi:[0,0,0]
	v_mfma_scale_f32_16x16x128_f8f6f4 v[144:147], v[192:199], v[200:207], v[144:147], v187, v187 op_sel_hi:[0,0,0]
	v_mfma_scale_f32_16x16x128_f8f6f4 v[124:127], v[10:17], v[208:215], v[124:127], v187, v187 op_sel_hi:[0,0,0]
	v_mfma_scale_f32_16x16x128_f8f6f4 v[128:131], v[192:199], v[208:215], v[128:131], v187, v187 op_sel_hi:[0,0,0]
	v_mfma_scale_f32_16x16x128_f8f6f4 v[108:111], v[10:17], v[226:233], v[108:111], v187, v187 op_sel_hi:[0,0,0]
	v_mfma_scale_f32_16x16x128_f8f6f4 v[112:115], v[192:199], v[226:233], v[112:115], v187, v187 op_sel_hi:[0,0,0]
	v_mfma_scale_f32_16x16x128_f8f6f4 v[76:79], v[10:17], v[234:241], v[76:79], v187, v187 op_sel_hi:[0,0,0]
	v_mfma_scale_f32_16x16x128_f8f6f4 v[84:87], v[192:199], v[234:241], v[84:87], v187, v187 op_sel_hi:[0,0,0]
	s_setprio 0
	s_setprio 1
	v_mfma_scale_f32_16x16x128_f8f6f4 v[148:151], v[2:9], v[200:207], v[148:151], v187, v187 op_sel_hi:[0,0,0]
	v_mfma_scale_f32_16x16x128_f8f6f4 v[152:155], v[18:25], v[200:207], v[152:155], v187, v187 op_sel_hi:[0,0,0]
	v_mfma_scale_f32_16x16x128_f8f6f4 v[132:135], v[2:9], v[208:215], v[132:135], v187, v187 op_sel_hi:[0,0,0]
	v_mfma_scale_f32_16x16x128_f8f6f4 v[136:139], v[18:25], v[208:215], v[136:139], v187, v187 op_sel_hi:[0,0,0]
	v_mfma_scale_f32_16x16x128_f8f6f4 v[116:119], v[2:9], v[226:233], v[116:119], v187, v187 op_sel_hi:[0,0,0]
	v_mfma_scale_f32_16x16x128_f8f6f4 v[120:123], v[18:25], v[226:233], v[120:123], v187, v187 op_sel_hi:[0,0,0]
	v_mfma_scale_f32_16x16x128_f8f6f4 v[96:99], v[2:9], v[234:241], v[96:99], v187, v187 op_sel_hi:[0,0,0]
	v_mfma_scale_f32_16x16x128_f8f6f4 v[104:107], v[18:25], v[234:241], v[104:107], v187, v187 op_sel_hi:[0,0,0]
	s_barrier
	s_setprio 0
	s_add_i32 s58, s74, s8
	v_lshl_add_u64 v[178:179], v[178:179], 0, s[82:83]
	s_mov_b32 m0, s58
	ds_read_b128 v[200:203], v191 offset:49152
	ds_read_b128 v[204:207], v191 offset:50176
	ds_read_b128 v[208:211], v191 offset:51200
	ds_read_b128 v[212:215], v191 offset:52224
	ds_read_b128 v[226:229], v191 offset:53248
	ds_read_b128 v[230:233], v191 offset:54272
	ds_read_b128 v[234:237], v191 offset:55296
	ds_read_b128 v[238:241], v191 offset:56320
	global_load_lds_dwordx4 v[178:179], off
	s_add_i32 m0, s58, 0x2000
	s_add_u32 s54, s54, 0x20080
	v_lshl_add_u64 v[178:179], v[180:181], 0, s[82:83]
	s_addc_u32 s55, s55, 0
	s_add_i32 s12, s12, s8
	global_load_lds_dwordx4 v[178:179], off
	v_lshl_add_u64 v[178:179], s[54:55], 0, v[158:159]
	s_mov_b32 m0, s12
	s_nop 0
	global_load_lds_dwordx4 v[178:179], off
	v_lshl_add_u64 v[178:179], s[54:55], 0, v[162:163]
	s_add_i32 m0, s12, 0x2000
	s_nop 0
	global_load_lds_dwordx4 v[178:179], off
	v_lshl_add_u64 v[178:179], v[182:183], 0, s[82:83]
	s_mov_b32 m0, s23
	s_nop 0
	global_load_lds_dwordx4 v[178:179], off
	v_lshl_add_u64 v[178:179], v[184:185], 0, s[82:83]
	s_mov_b32 m0, s26
	s_nop 0
	global_load_lds_dwordx4 v[178:179], off
	s_waitcnt vmcnt(8)
	s_waitcnt lgkmcnt(0)
	s_setprio 1
	s_barrier
	v_mfma_scale_f32_16x16x128_f8f6f4 v[80:83], v[10:17], v[200:207], v[80:83], v187, v187 op_sel_hi:[0,0,0]
	v_mfma_scale_f32_16x16x128_f8f6f4 v[88:91], v[192:199], v[200:207], v[88:91], v187, v187 op_sel_hi:[0,0,0]
	v_mfma_scale_f32_16x16x128_f8f6f4 v[60:63], v[10:17], v[208:215], v[60:63], v187, v187 op_sel_hi:[0,0,0]
	v_mfma_scale_f32_16x16x128_f8f6f4 v[64:67], v[192:199], v[208:215], v[64:67], v187, v187 op_sel_hi:[0,0,0]
	v_mfma_scale_f32_16x16x128_f8f6f4 v[44:47], v[10:17], v[226:233], v[44:47], v187, v187 op_sel_hi:[0,0,0]
	v_mfma_scale_f32_16x16x128_f8f6f4 v[48:51], v[192:199], v[226:233], v[48:51], v187, v187 op_sel_hi:[0,0,0]
	v_mfma_scale_f32_16x16x128_f8f6f4 v[28:31], v[10:17], v[234:241], v[28:31], v187, v187 op_sel_hi:[0,0,0]
	v_mfma_scale_f32_16x16x128_f8f6f4 v[32:35], v[192:199], v[234:241], v[32:35], v187, v187 op_sel_hi:[0,0,0]
	s_setprio 0
	s_setprio 1
	v_mfma_scale_f32_16x16x128_f8f6f4 v[92:95], v[2:9], v[200:207], v[92:95], v187, v187 op_sel_hi:[0,0,0]
	v_mfma_scale_f32_16x16x128_f8f6f4 v[100:103], v[18:25], v[200:207], v[100:103], v187, v187 op_sel_hi:[0,0,0]
	v_mfma_scale_f32_16x16x128_f8f6f4 v[68:71], v[2:9], v[208:215], v[68:71], v187, v187 op_sel_hi:[0,0,0]
	v_mfma_scale_f32_16x16x128_f8f6f4 v[72:75], v[18:25], v[208:215], v[72:75], v187, v187 op_sel_hi:[0,0,0]
	v_mfma_scale_f32_16x16x128_f8f6f4 v[52:55], v[2:9], v[226:233], v[52:55], v187, v187 op_sel_hi:[0,0,0]
	v_mfma_scale_f32_16x16x128_f8f6f4 v[56:59], v[18:25], v[226:233], v[56:59], v187, v187 op_sel_hi:[0,0,0]
	v_mfma_scale_f32_16x16x128_f8f6f4 v[36:39], v[2:9], v[234:241], v[36:39], v187, v187 op_sel_hi:[0,0,0]
	v_mfma_scale_f32_16x16x128_f8f6f4 v[40:43], v[18:25], v[234:241], v[40:43], v187, v187 op_sel_hi:[0,0,0]
	s_barrier
	s_setprio 0
	s_add_i32 s68, s68, 2
	s_add_u32 s52, s52, 0x100
	s_addc_u32 s53, s53, 0
	s_add_u32 s35, s35, 0x100
	s_addc_u32 s47, s47, 0

.LBB0_386:
	v_readlane_b32 s4, v253, 54
	v_readlane_b32 s5, v253, 55
	s_mov_b32 s52, s4
	s_ashr_i32 s53, s4, 31
	v_writelane_b32 v253, s4, 54
	s_lshl_b32 s12, s34, 2
	s_and_b32 s12, s12, 28
	v_writelane_b32 v253, s5, 55
	s_ashr_i32 s36, s34, 3
	v_readlane_b32 s4, v253, 52
	s_add_i32 s54, s4, s12
	s_ashr_i32 s37, s36, 31
	s_ashr_i32 s55, s54, 31
	s_ashr_i32 s35, s34, 31
	s_lshl_b64 s[36:37], s[36:37], 23
	s_lshl_b64 s[52:53], s[52:53], 21
	s_lshl_b64 s[54:55], s[54:55], 16
	s_lshl_b64 s[34:35], s[34:35], 14
	v_mov_b32_e32 v2, v189
	s_add_u32 s34, s57, s34
	s_nop 15
	s_nop 7
	s_addc_u32 s35, s15, s35
	v_lshl_or_b32 v26, v2, 6, v188
	global_load_dwordx4 v[2:5], v26, s[34:35]
	global_load_dwordx4 v[182:185], v26, s[34:35] offset:1024
	global_load_dwordx4 v[22:25], v26, s[34:35] offset:2048
	global_load_dwordx4 v[18:21], v26, s[34:35] offset:3072
	v_and_b32_e32 v7, 64, v224
	v_xor_b32_e32 v6, 16, v224
	v_add_u32_e32 v7, 64, v7
	v_xor_b32_e32 v8, 32, v224
	v_cmp_lt_i32_e32 vcc, v6, v7
	s_add_u32 s12, s50, s36
	s_waitcnt vmcnt(0)
	v_add_f32_e32 v22, v22, v23
	v_cndmask_b32_e32 v6, v224, v6, vcc
	v_cmp_lt_i32_e32 vcc, v8, v7
	v_add_f32_e32 v2, v2, v3
	v_add_f32_e32 v3, v4, v5
	v_cndmask_b32_e32 v7, v224, v8, vcc
	v_lshlrev_b32_e32 v181, 2, v6
	v_lshlrev_b32_e32 v180, 2, v7
	v_lshl_add_u64 v[6:7], s[34:35], 0, v[26:27]
	v_add_f32_e32 v26, v2, v3
	ds_bpermute_b32 v192, v181, v26
	v_add_co_u32_e32 v178, vcc, s6, v6
	s_addc_u32 s34, s51, s37
	s_nop 0
	v_addc_co_u32_e32 v179, vcc, 0, v7, vcc
	s_waitcnt lgkmcnt(0)
	v_add_f32_e32 v26, v26, v192
	global_load_dwordx4 v[14:17], v[178:179], off
	global_load_dwordx4 v[10:13], v[178:179], off offset:1024
	global_load_dwordx4 v[6:9], v[178:179], off offset:2048
	global_load_dwordx4 v[2:5], v[178:179], off offset:3072
	ds_bpermute_b32 v178, v180, v26
	s_add_u32 s12, s12, s52
	s_addc_u32 s34, s34, s53
	s_add_u32 s12, s12, s54
	s_addc_u32 s35, s34, s55
	s_waitcnt lgkmcnt(0)
	v_add_f32_e32 v26, v26, v178
	v_fmamk_f32 v26, v26, 0x3a800000, v222
	v_rsq_f32_e32 v26, v26
	s_add_u32 s34, s12, s27
	s_addc_u32 s35, s35, s46
	v_lshl_add_u64 v[178:179], s[34:35], 0, v[164:165]
	v_mul_f32_e32 v26, 0xbcb8aa3b, v26
	v_mul_f32_e32 v140, v140, v26
	v_mul_f32_e32 v144, v144, v26
	v_mul_f32_e32 v141, v141, v26
	v_mul_f32_e32 v145, v145, v26
	v_exp_f32_e32 v140, v140
	v_exp_f32_e32 v144, v144
	v_mul_f32_e32 v142, v142, v26
	v_mul_f32_e32 v146, v146, v26
	v_exp_f32_e32 v141, v141
	v_exp_f32_e32 v145, v145
	v_mul_f32_e32 v143, v143, v26
	v_mul_f32_e32 v147, v147, v26
	v_exp_f32_e32 v142, v142
	v_exp_f32_e32 v146, v146
	v_exp_f32_e32 v143, v143
	v_exp_f32_e32 v147, v147
	v_fmamk_f32 v140, v140, 0x3b808081, v223
	v_fmamk_f32 v144, v144, 0x3b808081, v223
	v_fmamk_f32 v141, v141, 0x3b808081, v223
	v_fmamk_f32 v145, v145, 0x3b808081, v223
	v_rcp_f32_e32 v140, v140
	v_rcp_f32_e32 v144, v144
	v_fmamk_f32 v142, v142, 0x3b808081, v223
	v_fmamk_f32 v146, v146, 0x3b808081, v223
	v_rcp_f32_e32 v141, v141
	v_rcp_f32_e32 v145, v145
	v_fmamk_f32 v143, v143, 0x3b808081, v223
	v_fmamk_f32 v147, v147, 0x3b808081, v223
	v_rcp_f32_e32 v142, v142
	v_rcp_f32_e32 v146, v146
	v_rcp_f32_e32 v143, v143
	v_rcp_f32_e32 v147, v147
	v_cvt_pk_u8_f32 v140, v140, 0, 0
	v_cvt_pk_u8_f32 v144, v144, 0, 0
	v_cvt_pk_u8_f32 v140, v141, 1, v140
	v_cvt_pk_u8_f32 v141, v145, 1, v144
	v_cvt_pk_u8_f32 v140, v142, 2, v140
	v_cvt_pk_u8_f32 v141, v146, 2, v141
	v_cvt_pk_u8_f32 v140, v143, 3, v140
	v_cvt_pk_u8_f32 v141, v147, 3, v141
	v_add_u32_e32 v142, 0xfefefeff, v140
	v_add_u32_e32 v143, 0xfefefeff, v141
	v_bitop3_b32 v142, v142, v140, v142 bitop3:0x30
	v_bitop3_b32 v143, v143, v141, v143 bitop3:0x30
	v_mul_f32_e32 v148, v148, v26
	v_lshrrev_b32_e32 v142, 7, v142
	v_lshrrev_b32_e32 v143, 7, v143
	v_mul_f32_e32 v149, v149, v26
	v_exp_f32_e32 v148, v148
	v_and_or_b32 v140, v142, s9, v140
	v_and_or_b32 v141, v143, s9, v141
	v_exp_f32_e32 v149, v149
	global_store_dwordx2 v[178:179], v[140:141], off
	v_mul_f32_e32 v140, v150, v26
	v_exp_f32_e32 v140, v140
	v_fmamk_f32 v148, v148, 0x3b808081, v223
	v_fmamk_f32 v149, v149, 0x3b808081, v223
	v_rcp_f32_e32 v148, v148
	v_mul_f32_e32 v152, v152, v26
	v_rcp_f32_e32 v149, v149
	v_fmamk_f32 v140, v140, 0x3b808081, v223
	v_mul_f32_e32 v143, v154, v26
	v_mul_f32_e32 v144, v151, v26
	v_mul_f32_e32 v153, v153, v26
	v_exp_f32_e32 v152, v152
	v_rcp_f32_e32 v140, v140
	v_exp_f32_e32 v143, v143
	v_exp_f32_e32 v144, v144
	v_exp_f32_e32 v153, v153
	v_cvt_pk_u8_f32 v148, v148, 0, 0
	v_cvt_pk_u8_f32 v142, v149, 1, v148
	v_fmamk_f32 v152, v152, 0x3b808081, v223
	v_cvt_pk_u8_f32 v140, v140, 2, v142
	v_fmamk_f32 v142, v143, 0x3b808081, v223
	v_fmamk_f32 v143, v144, 0x3b808081, v223
	v_add_f32_e32 v144, v182, v183
	v_add_f32_e32 v145, v184, v185
	v_fmamk_f32 v153, v153, 0x3b808081, v223
	v_rcp_f32_e32 v152, v152
	v_add_f32_e32 v144, v144, v145
	v_rcp_f32_e32 v153, v153
	ds_bpermute_b32 v145, v181, v144
	v_rcp_f32_e32 v142, v142
	v_rcp_f32_e32 v143, v143
	v_cvt_pk_u8_f32 v141, v152, 0, 0
	v_cvt_pk_u8_f32 v141, v153, 1, v141
	v_cvt_pk_u8_f32 v141, v142, 2, v141
	s_waitcnt lgkmcnt(0)
	v_add_f32_e32 v142, v144, v145
	v_cvt_pk_u8_f32 v140, v143, 3, v140
	ds_bpermute_b32 v143, v180, v142
	v_mul_f32_e32 v26, v155, v26
	v_exp_f32_e32 v26, v26
	v_add_f32_e32 v23, v24, v25
	v_add_f32_e32 v22, v22, v23
	s_waitcnt lgkmcnt(0)
	v_add_f32_e32 v142, v142, v143
	v_fmamk_f32 v26, v26, 0x3b808081, v223
	v_fmamk_f32 v142, v142, 0x3a800000, v222
	v_rcp_f32_e32 v26, v26
	v_rsq_f32_e32 v142, v142
	ds_bpermute_b32 v23, v181, v22
	v_add_f32_e32 v18, v18, v19
	v_cvt_pk_u8_f32 v26, v26, 3, v141
	v_add_u32_e32 v141, 0xfefefeff, v140
	v_mul_f32_e32 v142, 0xbcb8aa3b, v142
	v_bitop3_b32 v141, v141, v140, v141 bitop3:0x30
	v_mul_f32_e32 v124, v124, v142
	v_lshrrev_b32_e32 v141, 7, v141
	v_exp_f32_e32 v124, v124
	v_mul_f32_e32 v125, v125, v142
	v_and_or_b32 v140, v141, s9, v140
	v_add_u32_e32 v141, 0xfefefeff, v26
	v_exp_f32_e32 v125, v125
	v_bitop3_b32 v141, v141, v26, v141 bitop3:0x30
	v_lshrrev_b32_e32 v141, 7, v141
	v_and_or_b32 v141, v141, s9, v26
	v_fmamk_f32 v26, v124, 0x3b808081, v223
	v_mul_f32_e32 v124, v128, v142
	v_exp_f32_e32 v124, v124
	v_rcp_f32_e32 v26, v26
	v_fmamk_f32 v125, v125, 0x3b808081, v223
	v_mul_f32_e32 v128, v129, v142
	v_rcp_f32_e32 v125, v125
	v_exp_f32_e32 v128, v128
	v_fmamk_f32 v124, v124, 0x3b808081, v223
	v_cvt_pk_u8_f32 v26, v26, 0, 0
	v_rcp_f32_e32 v124, v124
	v_cvt_pk_u8_f32 v26, v125, 1, v26
	v_fmamk_f32 v125, v128, 0x3b808081, v223
	v_mul_f32_e32 v126, v126, v142
	v_mul_f32_e32 v128, v130, v142
	v_rcp_f32_e32 v125, v125
	v_exp_f32_e32 v126, v126
	v_exp_f32_e32 v128, v128
	v_cvt_pk_u8_f32 v124, v124, 0, 0
	v_cvt_pk_u8_f32 v124, v125, 1, v124
	v_fmamk_f32 v125, v126, 0x3b808081, v223
	v_fmamk_f32 v126, v128, 0x3b808081, v223
	v_mul_f32_e32 v127, v127, v142
	v_mul_f32_e32 v128, v131, v142
	v_exp_f32_e32 v127, v127
	v_exp_f32_e32 v128, v128
	v_rcp_f32_e32 v125, v125
	v_rcp_f32_e32 v126, v126
	v_fmamk_f32 v127, v127, 0x3b808081, v223
	v_fmamk_f32 v128, v128, 0x3b808081, v223
	v_rcp_f32_e32 v127, v127
	v_rcp_f32_e32 v128, v128
	v_cvt_pk_u8_f32 v26, v125, 2, v26
	v_cvt_pk_u8_f32 v124, v126, 2, v124
	v_cvt_pk_u8_f32 v26, v127, 3, v26
	v_cvt_pk_u8_f32 v125, v128, 3, v124
	v_add_u32_e32 v124, 0xfefefeff, v26
	v_add_u32_e32 v126, 0xfefefeff, v125
	v_bitop3_b32 v124, v124, v26, v124 bitop3:0x30
	v_bitop3_b32 v126, v126, v125, v126 bitop3:0x30
	v_lshrrev_b32_e32 v124, 7, v124
	v_lshrrev_b32_e32 v126, 7, v126
	v_and_or_b32 v124, v124, s9, v26
	v_mul_f32_e32 v26, v132, v142
	v_mul_f32_e32 v127, v136, v142
	v_and_or_b32 v125, v126, s9, v125
	v_exp_f32_e32 v26, v26
	v_exp_f32_e32 v127, v127
	global_store_dwordx2 v[178:179], v[124:125], off offset:1024
	v_mul_f32_e32 v125, v133, v142
	v_mul_f32_e32 v126, v137, v142
	v_exp_f32_e32 v125, v125
	v_exp_f32_e32 v126, v126
	v_fmamk_f32 v26, v26, 0x3b808081, v223
	v_fmamk_f32 v124, v127, 0x3b808081, v223
	v_rcp_f32_e32 v26, v26
	v_rcp_f32_e32 v124, v124
	v_fmamk_f32 v125, v125, 0x3b808081, v223
	v_fmamk_f32 v126, v126, 0x3b808081, v223
	v_mul_f32_e32 v127, v134, v142
	v_rcp_f32_e32 v125, v125
	v_rcp_f32_e32 v126, v126
	v_exp_f32_e32 v127, v127
	v_cvt_pk_u8_f32 v26, v26, 0, 0
	v_cvt_pk_u8_f32 v124, v124, 0, 0
	v_cvt_pk_u8_f32 v26, v125, 1, v26
	v_cvt_pk_u8_f32 v124, v126, 1, v124
	v_fmamk_f32 v125, v127, 0x3b808081, v223
	v_mul_f32_e32 v126, v138, v142
	v_mul_f32_e32 v127, v135, v142
	v_rcp_f32_e32 v125, v125
	v_exp_f32_e32 v126, v126
	v_exp_f32_e32 v127, v127
	s_waitcnt lgkmcnt(0)
	v_add_f32_e32 v22, v22, v23
	v_cvt_pk_u8_f32 v26, v125, 2, v26
	v_fmamk_f32 v125, v126, 0x3b808081, v223
	v_fmamk_f32 v126, v127, 0x3b808081, v223
	v_mul_f32_e32 v127, v139, v142
	v_exp_f32_e32 v127, v127
	ds_bpermute_b32 v23, v180, v22
	v_rcp_f32_e32 v125, v125
	v_rcp_f32_e32 v126, v126
	v_fmamk_f32 v25, v127, 0x3b808081, v223
	v_rcp_f32_e32 v25, v25
	s_waitcnt lgkmcnt(0)
	v_add_f32_e32 v22, v22, v23
	v_fmamk_f32 v22, v22, 0x3a800000, v222
	v_cvt_pk_u8_f32 v24, v125, 2, v124
	v_cvt_pk_u8_f32 v26, v126, 3, v26
	v_rsq_f32_e32 v23, v22
	v_cvt_pk_u8_f32 v24, v25, 3, v24
	v_add_u32_e32 v25, 0xfefefeff, v26
	v_bitop3_b32 v25, v25, v26, v25 bitop3:0x30
	v_lshrrev_b32_e32 v25, 7, v25
	v_and_or_b32 v22, v25, s9, v26
	v_add_u32_e32 v25, 0xfefefeff, v24
	v_mul_f32_e32 v26, 0xbcb8aa3b, v23
	v_bitop3_b32 v25, v25, v24, v25 bitop3:0x30
	v_mul_f32_e32 v23, v108, v26
	v_exp_f32_e32 v108, v23
	v_lshrrev_b32_e32 v23, 7, v25
	v_and_or_b32 v23, v23, s9, v24
	v_mul_f32_e32 v24, v109, v26
	v_exp_f32_e32 v24, v24
	global_store_dwordx2 v[178:179], v[22:23], off offset:1536
	v_fmamk_f32 v22, v108, 0x3b808081, v223
	v_mul_f32_e32 v23, v112, v26
	v_exp_f32_e32 v23, v23
	v_rcp_f32_e32 v22, v22
	v_fmamk_f32 v24, v24, 0x3b808081, v223
	v_mul_f32_e32 v25, v113, v26
	v_rcp_f32_e32 v24, v24
	v_exp_f32_e32 v25, v25
	v_fmamk_f32 v23, v23, 0x3b808081, v223
	v_cvt_pk_u8_f32 v22, v22, 0, 0
	v_rcp_f32_e32 v23, v23
	v_cvt_pk_u8_f32 v22, v24, 1, v22
	v_fmamk_f32 v24, v25, 0x3b808081, v223
	v_mul_f32_e32 v25, v110, v26
	v_mul_f32_e32 v108, v114, v26
	v_rcp_f32_e32 v24, v24
	v_exp_f32_e32 v25, v25
	v_exp_f32_e32 v108, v108
	v_cvt_pk_u8_f32 v23, v23, 0, 0
	v_cvt_pk_u8_f32 v23, v24, 1, v23
	v_fmamk_f32 v24, v25, 0x3b808081, v223
	v_fmamk_f32 v25, v108, 0x3b808081, v223
	v_mul_f32_e32 v108, v111, v26
	v_exp_f32_e32 v108, v108
	v_rcp_f32_e32 v24, v24
	v_mul_f32_e32 v109, v115, v26
	v_exp_f32_e32 v109, v109
	v_fmamk_f32 v108, v108, 0x3b808081, v223
	v_rcp_f32_e32 v108, v108
	v_cvt_pk_u8_f32 v22, v24, 2, v22
	v_rcp_f32_e32 v25, v25
	v_fmamk_f32 v109, v109, 0x3b808081, v223
	v_cvt_pk_u8_f32 v22, v108, 3, v22
	v_add_u32_e32 v24, 0xfefefeff, v22
	v_bitop3_b32 v24, v24, v22, v24 bitop3:0x30
	v_lshrrev_b32_e32 v24, 7, v24
	v_and_or_b32 v22, v24, s9, v22
	v_mul_f32_e32 v24, v116, v26
	v_rcp_f32_e32 v109, v109
	v_exp_f32_e32 v24, v24
	v_cvt_pk_u8_f32 v23, v25, 2, v23
	v_mul_f32_e32 v108, v120, v26
	v_cvt_pk_u8_f32 v23, v109, 3, v23
	v_fmamk_f32 v24, v24, 0x3b808081, v223
	v_add_u32_e32 v25, 0xfefefeff, v23
	v_rcp_f32_e32 v24, v24
	v_bitop3_b32 v25, v25, v23, v25 bitop3:0x30
	v_lshrrev_b32_e32 v25, 7, v25
	v_and_or_b32 v23, v25, s9, v23
	v_exp_f32_e32 v108, v108
	global_store_dwordx2 v[178:179], v[22:23], off offset:2048
	v_cvt_pk_u8_f32 v22, v24, 0, 0
	v_mul_f32_e32 v24, v117, v26
	v_mul_f32_e32 v25, v121, v26
	v_exp_f32_e32 v24, v24
	v_exp_f32_e32 v25, v25
	v_fmamk_f32 v23, v108, 0x3b808081, v223
	v_rcp_f32_e32 v23, v23
	v_fmamk_f32 v24, v24, 0x3b808081, v223
	v_fmamk_f32 v25, v25, 0x3b808081, v223
	v_mul_f32_e32 v108, v118, v26
	v_add_f32_e32 v19, v20, v21
	v_rcp_f32_e32 v24, v24
	v_rcp_f32_e32 v25, v25
	v_exp_f32_e32 v108, v108
	v_add_f32_e32 v18, v18, v19
	ds_bpermute_b32 v19, v181, v18
	v_cvt_pk_u8_f32 v23, v23, 0, 0
	v_cvt_pk_u8_f32 v22, v24, 1, v22
	v_cvt_pk_u8_f32 v23, v25, 1, v23
	v_fmamk_f32 v24, v108, 0x3b808081, v223
	v_mul_f32_e32 v25, v122, v26
	v_mul_f32_e32 v108, v119, v26
	v_rcp_f32_e32 v24, v24
	v_exp_f32_e32 v25, v25
	v_exp_f32_e32 v108, v108
	v_mul_f32_e32 v26, v123, v26
	v_exp_f32_e32 v26, v26
	s_waitcnt lgkmcnt(0)
	v_add_f32_e32 v18, v18, v19
	ds_bpermute_b32 v19, v180, v18
	v_cvt_pk_u8_f32 v22, v24, 2, v22
	v_fmamk_f32 v24, v25, 0x3b808081, v223
	v_fmamk_f32 v25, v108, 0x3b808081, v223
	v_rcp_f32_e32 v24, v24
	v_rcp_f32_e32 v25, v25
	v_fmamk_f32 v21, v26, 0x3b808081, v223
	v_rcp_f32_e32 v21, v21
	s_waitcnt lgkmcnt(0)
	v_add_f32_e32 v18, v18, v19
	v_fmamk_f32 v18, v18, 0x3a800000, v222
	v_cvt_pk_u8_f32 v20, v24, 2, v23
	v_cvt_pk_u8_f32 v22, v25, 3, v22
	v_rsq_f32_e32 v19, v18
	v_cvt_pk_u8_f32 v20, v21, 3, v20
	v_add_u32_e32 v21, 0xfefefeff, v22
	v_bitop3_b32 v21, v21, v22, v21 bitop3:0x30
	v_lshrrev_b32_e32 v21, 7, v21
	v_and_or_b32 v18, v21, s9, v22
	v_add_u32_e32 v21, 0xfefefeff, v20
	v_mul_f32_e32 v22, 0xbcb8aa3b, v19
	v_bitop3_b32 v21, v21, v20, v21 bitop3:0x30
	v_mul_f32_e32 v19, v76, v22
	v_exp_f32_e32 v23, v19
	v_lshrrev_b32_e32 v19, 7, v21
	v_and_or_b32 v19, v19, s9, v20
	v_mul_f32_e32 v20, v77, v22
	v_exp_f32_e32 v20, v20
	global_store_dwordx2 v[178:179], v[18:19], off offset:2560
	v_fmamk_f32 v18, v23, 0x3b808081, v223
	v_mul_f32_e32 v19, v84, v22
	v_exp_f32_e32 v19, v19
	v_rcp_f32_e32 v18, v18
	v_fmamk_f32 v20, v20, 0x3b808081, v223
	v_mul_f32_e32 v21, v85, v22
	v_rcp_f32_e32 v20, v20
	v_exp_f32_e32 v21, v21
	v_fmamk_f32 v19, v19, 0x3b808081, v223
	v_cvt_pk_u8_f32 v18, v18, 0, 0
	v_rcp_f32_e32 v19, v19
	v_cvt_pk_u8_f32 v18, v20, 1, v18
	v_fmamk_f32 v20, v21, 0x3b808081, v223
	v_mul_f32_e32 v21, v78, v22
	v_mul_f32_e32 v23, v86, v22
	v_rcp_f32_e32 v20, v20
	v_exp_f32_e32 v21, v21
	v_exp_f32_e32 v23, v23
	v_cvt_pk_u8_f32 v19, v19, 0, 0
	v_cvt_pk_u8_f32 v19, v20, 1, v19
	v_fmamk_f32 v20, v21, 0x3b808081, v223
	v_fmamk_f32 v21, v23, 0x3b808081, v223
	v_mul_f32_e32 v23, v79, v22
	v_exp_f32_e32 v23, v23
	v_rcp_f32_e32 v20, v20
	v_mul_f32_e32 v24, v87, v22
	v_exp_f32_e32 v24, v24
	v_fmamk_f32 v23, v23, 0x3b808081, v223
	v_rcp_f32_e32 v23, v23
	v_cvt_pk_u8_f32 v18, v20, 2, v18
	v_rcp_f32_e32 v21, v21
	v_fmamk_f32 v24, v24, 0x3b808081, v223
	v_cvt_pk_u8_f32 v18, v23, 3, v18
	v_add_u32_e32 v20, 0xfefefeff, v18
	v_bitop3_b32 v20, v20, v18, v20 bitop3:0x30
	v_lshrrev_b32_e32 v20, 7, v20
	v_and_or_b32 v18, v20, s9, v18
	v_mul_f32_e32 v20, v96, v22
	v_rcp_f32_e32 v24, v24
	v_exp_f32_e32 v20, v20
	v_cvt_pk_u8_f32 v19, v21, 2, v19
	v_mul_f32_e32 v23, v104, v22
	v_cvt_pk_u8_f32 v19, v24, 3, v19
	v_fmamk_f32 v20, v20, 0x3b808081, v223
	v_add_u32_e32 v21, 0xfefefeff, v19
	v_rcp_f32_e32 v20, v20
	v_bitop3_b32 v21, v21, v19, v21 bitop3:0x30
	v_lshrrev_b32_e32 v21, 7, v21
	v_and_or_b32 v19, v21, s9, v19
	v_exp_f32_e32 v23, v23
	global_store_dwordx2 v[178:179], v[18:19], off offset:3072
	v_cvt_pk_u8_f32 v18, v20, 0, 0
	v_mul_f32_e32 v20, v97, v22
	v_mul_f32_e32 v21, v105, v22
	v_exp_f32_e32 v20, v20
	v_exp_f32_e32 v21, v21
	v_fmamk_f32 v19, v23, 0x3b808081, v223
	v_rcp_f32_e32 v19, v19
	v_fmamk_f32 v20, v20, 0x3b808081, v223
	v_fmamk_f32 v21, v21, 0x3b808081, v223
	v_mul_f32_e32 v23, v98, v22
	s_waitcnt vmcnt(9)
	v_add_f32_e32 v14, v14, v15
	v_add_f32_e32 v15, v16, v17
	v_rcp_f32_e32 v20, v20
	v_rcp_f32_e32 v21, v21
	v_exp_f32_e32 v23, v23
	v_add_f32_e32 v14, v14, v15
	ds_bpermute_b32 v15, v181, v14
	v_cvt_pk_u8_f32 v19, v19, 0, 0
	v_cvt_pk_u8_f32 v18, v20, 1, v18
	v_cvt_pk_u8_f32 v19, v21, 1, v19
	v_fmamk_f32 v20, v23, 0x3b808081, v223
	v_mul_f32_e32 v21, v106, v22
	v_mul_f32_e32 v23, v99, v22
	v_rcp_f32_e32 v20, v20
	v_exp_f32_e32 v21, v21
	v_exp_f32_e32 v23, v23
	v_mul_f32_e32 v22, v107, v22
	v_exp_f32_e32 v22, v22
	s_waitcnt lgkmcnt(0)
	v_add_f32_e32 v14, v14, v15
	ds_bpermute_b32 v15, v180, v14
	v_cvt_pk_u8_f32 v18, v20, 2, v18
	v_fmamk_f32 v20, v21, 0x3b808081, v223
	v_fmamk_f32 v21, v23, 0x3b808081, v223
	v_rcp_f32_e32 v20, v20
	v_rcp_f32_e32 v21, v21
	v_fmamk_f32 v17, v22, 0x3b808081, v223
	v_rcp_f32_e32 v17, v17
	s_waitcnt lgkmcnt(0)
	v_add_f32_e32 v14, v14, v15
	v_fmamk_f32 v14, v14, 0x3a800000, v222
	v_cvt_pk_u8_f32 v16, v20, 2, v19
	v_cvt_pk_u8_f32 v18, v21, 3, v18
	v_rsq_f32_e32 v15, v14
	v_cvt_pk_u8_f32 v16, v17, 3, v16
	v_add_u32_e32 v17, 0xfefefeff, v18
	v_bitop3_b32 v17, v17, v18, v17 bitop3:0x30
	v_lshrrev_b32_e32 v17, 7, v17
	v_and_or_b32 v14, v17, s9, v18
	v_add_u32_e32 v17, 0xfefefeff, v16
	v_mul_f32_e32 v18, 0xbcb8aa3b, v15
	v_bitop3_b32 v17, v17, v16, v17 bitop3:0x30
	v_mul_f32_e32 v15, v80, v18
	v_exp_f32_e32 v19, v15
	v_lshrrev_b32_e32 v15, 7, v17
	v_and_or_b32 v15, v15, s9, v16
	v_mul_f32_e32 v16, v81, v18
	v_exp_f32_e32 v16, v16
	global_store_dwordx2 v[178:179], v[14:15], off offset:3584
	v_fmamk_f32 v14, v19, 0x3b808081, v223
	v_mul_f32_e32 v15, v88, v18
	v_exp_f32_e32 v15, v15
	v_rcp_f32_e32 v14, v14
	v_fmamk_f32 v16, v16, 0x3b808081, v223
	v_mul_f32_e32 v17, v89, v18
	v_rcp_f32_e32 v16, v16
	v_exp_f32_e32 v17, v17
	v_fmamk_f32 v15, v15, 0x3b808081, v223
	v_cvt_pk_u8_f32 v14, v14, 0, 0
	v_rcp_f32_e32 v15, v15
	v_cvt_pk_u8_f32 v14, v16, 1, v14
	v_fmamk_f32 v16, v17, 0x3b808081, v223
	v_mul_f32_e32 v17, v82, v18
	v_mul_f32_e32 v19, v90, v18
	v_rcp_f32_e32 v16, v16
	v_exp_f32_e32 v17, v17
	v_exp_f32_e32 v19, v19
	v_cvt_pk_u8_f32 v15, v15, 0, 0
	v_cvt_pk_u8_f32 v15, v16, 1, v15
	v_fmamk_f32 v16, v17, 0x3b808081, v223
	v_fmamk_f32 v17, v19, 0x3b808081, v223
	v_mul_f32_e32 v19, v83, v18
	v_exp_f32_e32 v19, v19
	v_mul_f32_e32 v20, v91, v18
	v_exp_f32_e32 v20, v20
	v_rcp_f32_e32 v16, v16
	v_fmamk_f32 v19, v19, 0x3b808081, v223
	v_rcp_f32_e32 v19, v19
	v_rcp_f32_e32 v17, v17
	v_fmamk_f32 v20, v20, 0x3b808081, v223
	v_rcp_f32_e32 v20, v20
	v_cvt_pk_u8_f32 v14, v16, 2, v14
	v_cvt_pk_u8_f32 v14, v19, 3, v14
	v_add_u32_e32 v16, 0xfefefeff, v14
	v_cvt_pk_u8_f32 v15, v17, 2, v15
	v_bitop3_b32 v16, v16, v14, v16 bitop3:0x30
	v_mul_f32_e32 v17, v92, v18
	v_cvt_pk_u8_f32 v15, v20, 3, v15
	v_lshrrev_b32_e32 v16, 7, v16
	v_exp_f32_e32 v19, v17
	v_and_or_b32 v16, v16, s9, v14
	v_add_u32_e32 v14, 0xfefefeff, v15
	v_bitop3_b32 v14, v14, v15, v14 bitop3:0x30
	v_lshrrev_b32_e32 v14, 7, v14
	v_and_or_b32 v17, v14, s9, v15
	v_fmamk_f32 v14, v19, 0x3b808081, v223
	v_rcp_f32_e32 v19, v14
	v_mul_f32_e32 v14, v100, v18
	v_exp_f32_e32 v20, v14
	v_add_co_u32_e32 v14, vcc, s10, v178
	v_mul_f32_e32 v21, v94, v18
	s_nop 0
	v_addc_co_u32_e32 v15, vcc, 0, v179, vcc
	global_store_dwordx2 v[14:15], v[16:17], off
	v_cvt_pk_u8_f32 v16, v19, 0, 0
	v_fmamk_f32 v17, v20, 0x3b808081, v223
	v_mul_f32_e32 v19, v93, v18
	v_mul_f32_e32 v20, v101, v18
	v_exp_f32_e32 v19, v19
	v_exp_f32_e32 v20, v20
	v_rcp_f32_e32 v17, v17
	s_waitcnt vmcnt(10)
	v_add_f32_e32 v10, v10, v11
	v_fmamk_f32 v19, v19, 0x3b808081, v223
	v_fmamk_f32 v20, v20, 0x3b808081, v223
	v_add_f32_e32 v11, v12, v13
	v_rcp_f32_e32 v19, v19
	v_rcp_f32_e32 v20, v20
	v_exp_f32_e32 v21, v21
	v_add_f32_e32 v10, v10, v11
	ds_bpermute_b32 v11, v181, v10
	v_cvt_pk_u8_f32 v17, v17, 0, 0
	v_cvt_pk_u8_f32 v16, v19, 1, v16
	v_cvt_pk_u8_f32 v17, v20, 1, v17
	v_fmamk_f32 v19, v21, 0x3b808081, v223
	v_mul_f32_e32 v20, v102, v18
	v_mul_f32_e32 v21, v95, v18
	v_rcp_f32_e32 v19, v19
	v_exp_f32_e32 v20, v20
	v_exp_f32_e32 v21, v21
	v_mul_f32_e32 v18, v103, v18
	v_exp_f32_e32 v18, v18
	s_waitcnt lgkmcnt(0)
	v_add_f32_e32 v10, v10, v11
	ds_bpermute_b32 v11, v180, v10
	v_cvt_pk_u8_f32 v16, v19, 2, v16
	v_fmamk_f32 v19, v20, 0x3b808081, v223
	v_fmamk_f32 v20, v21, 0x3b808081, v223
	v_rcp_f32_e32 v19, v19
	v_rcp_f32_e32 v20, v20
	v_fmamk_f32 v13, v18, 0x3b808081, v223
	v_rcp_f32_e32 v13, v13
	s_waitcnt lgkmcnt(0)
	v_add_f32_e32 v10, v10, v11
	v_fmamk_f32 v10, v10, 0x3a800000, v222
	v_cvt_pk_u8_f32 v12, v19, 2, v17
	v_cvt_pk_u8_f32 v16, v20, 3, v16
	v_rsq_f32_e32 v11, v10
	v_cvt_pk_u8_f32 v12, v13, 3, v12
	v_add_u32_e32 v13, 0xfefefeff, v16
	v_bitop3_b32 v13, v13, v16, v13 bitop3:0x30
	v_lshrrev_b32_e32 v13, 7, v13
	v_and_or_b32 v10, v13, s9, v16
	v_add_u32_e32 v13, 0xfefefeff, v12
	v_mul_f32_e32 v16, 0xbcb8aa3b, v11
	v_bitop3_b32 v13, v13, v12, v13 bitop3:0x30
	v_mul_f32_e32 v11, v60, v16
	v_exp_f32_e32 v17, v11
	v_lshrrev_b32_e32 v11, 7, v13
	v_and_or_b32 v11, v11, s9, v12
	v_mul_f32_e32 v12, v61, v16
	v_exp_f32_e32 v12, v12
	global_store_dwordx2 v[14:15], v[10:11], off offset:512
	v_fmamk_f32 v10, v17, 0x3b808081, v223
	v_mul_f32_e32 v11, v64, v16
	v_exp_f32_e32 v11, v11
	v_rcp_f32_e32 v10, v10
	v_fmamk_f32 v12, v12, 0x3b808081, v223
	v_mul_f32_e32 v13, v65, v16
	v_rcp_f32_e32 v12, v12
	v_exp_f32_e32 v13, v13
	v_fmamk_f32 v11, v11, 0x3b808081, v223
	v_cvt_pk_u8_f32 v10, v10, 0, 0
	v_rcp_f32_e32 v11, v11
	v_cvt_pk_u8_f32 v10, v12, 1, v10
	v_fmamk_f32 v12, v13, 0x3b808081, v223
	v_mul_f32_e32 v13, v62, v16
	v_mul_f32_e32 v17, v66, v16
	v_rcp_f32_e32 v12, v12
	v_exp_f32_e32 v13, v13
	v_exp_f32_e32 v17, v17
	v_cvt_pk_u8_f32 v11, v11, 0, 0
	v_cvt_pk_u8_f32 v11, v12, 1, v11
	v_fmamk_f32 v12, v13, 0x3b808081, v223
	v_fmamk_f32 v13, v17, 0x3b808081, v223
	v_mul_f32_e32 v17, v63, v16
	v_exp_f32_e32 v17, v17
	v_rcp_f32_e32 v12, v12
	v_mul_f32_e32 v18, v67, v16
	v_exp_f32_e32 v18, v18
	v_fmamk_f32 v17, v17, 0x3b808081, v223
	v_rcp_f32_e32 v17, v17
	v_cvt_pk_u8_f32 v10, v12, 2, v10
	v_rcp_f32_e32 v13, v13
	v_fmamk_f32 v18, v18, 0x3b808081, v223
	v_cvt_pk_u8_f32 v10, v17, 3, v10
	v_add_u32_e32 v12, 0xfefefeff, v10
	v_bitop3_b32 v12, v12, v10, v12 bitop3:0x30
	v_lshrrev_b32_e32 v12, 7, v12
	v_and_or_b32 v10, v12, s9, v10
	v_mul_f32_e32 v12, v68, v16
	v_rcp_f32_e32 v18, v18
	v_exp_f32_e32 v12, v12
	v_cvt_pk_u8_f32 v11, v13, 2, v11
	v_mul_f32_e32 v17, v72, v16
	v_cvt_pk_u8_f32 v11, v18, 3, v11
	v_fmamk_f32 v12, v12, 0x3b808081, v223
	v_add_u32_e32 v13, 0xfefefeff, v11
	v_rcp_f32_e32 v12, v12
	v_bitop3_b32 v13, v13, v11, v13 bitop3:0x30
	v_lshrrev_b32_e32 v13, 7, v13
	v_and_or_b32 v11, v13, s9, v11
	v_exp_f32_e32 v17, v17
	global_store_dwordx2 v[14:15], v[10:11], off offset:1024
	v_cvt_pk_u8_f32 v10, v12, 0, 0
	v_mul_f32_e32 v12, v69, v16
	v_mul_f32_e32 v13, v73, v16
	v_exp_f32_e32 v12, v12
	v_exp_f32_e32 v13, v13
	v_fmamk_f32 v11, v17, 0x3b808081, v223
	v_rcp_f32_e32 v11, v11
	v_fmamk_f32 v12, v12, 0x3b808081, v223
	v_fmamk_f32 v13, v13, 0x3b808081, v223
	v_mul_f32_e32 v17, v70, v16
	s_waitcnt vmcnt(11)
	v_add_f32_e32 v6, v6, v7
	v_add_f32_e32 v7, v8, v9
	v_rcp_f32_e32 v12, v12
	v_rcp_f32_e32 v13, v13
	v_exp_f32_e32 v17, v17
	v_add_f32_e32 v6, v6, v7
	ds_bpermute_b32 v7, v181, v6
	v_cvt_pk_u8_f32 v11, v11, 0, 0
	v_cvt_pk_u8_f32 v10, v12, 1, v10
	v_cvt_pk_u8_f32 v11, v13, 1, v11
	v_fmamk_f32 v12, v17, 0x3b808081, v223
	v_mul_f32_e32 v13, v74, v16
	v_mul_f32_e32 v17, v71, v16
	v_rcp_f32_e32 v12, v12
	v_exp_f32_e32 v13, v13
	v_exp_f32_e32 v17, v17
	v_mul_f32_e32 v16, v75, v16
	v_exp_f32_e32 v16, v16
	s_waitcnt lgkmcnt(0)
	v_add_f32_e32 v6, v6, v7
	ds_bpermute_b32 v7, v180, v6
	v_cvt_pk_u8_f32 v10, v12, 2, v10
	v_fmamk_f32 v12, v13, 0x3b808081, v223
	v_fmamk_f32 v13, v17, 0x3b808081, v223
	v_rcp_f32_e32 v12, v12
	v_rcp_f32_e32 v13, v13
	v_fmamk_f32 v9, v16, 0x3b808081, v223
	v_rcp_f32_e32 v9, v9
	s_waitcnt lgkmcnt(0)
	v_add_f32_e32 v6, v6, v7
	v_fmamk_f32 v6, v6, 0x3a800000, v222
	v_cvt_pk_u8_f32 v8, v12, 2, v11
	v_cvt_pk_u8_f32 v10, v13, 3, v10
	v_rsq_f32_e32 v7, v6
	v_cvt_pk_u8_f32 v8, v9, 3, v8
	v_add_u32_e32 v9, 0xfefefeff, v10
	v_bitop3_b32 v9, v9, v10, v9 bitop3:0x30
	v_lshrrev_b32_e32 v9, 7, v9
	v_and_or_b32 v6, v9, s9, v10
	v_add_u32_e32 v9, 0xfefefeff, v8
	v_mul_f32_e32 v10, 0xbcb8aa3b, v7
	v_bitop3_b32 v9, v9, v8, v9 bitop3:0x30
	v_mul_f32_e32 v7, v44, v10
	v_exp_f32_e32 v11, v7
	v_lshrrev_b32_e32 v7, 7, v9
	v_and_or_b32 v7, v7, s9, v8
	v_mul_f32_e32 v8, v45, v10
	v_exp_f32_e32 v8, v8
	global_store_dwordx2 v[14:15], v[6:7], off offset:1536
	v_fmamk_f32 v6, v11, 0x3b808081, v223
	v_mul_f32_e32 v7, v48, v10
	v_exp_f32_e32 v7, v7
	v_rcp_f32_e32 v6, v6
	v_fmamk_f32 v8, v8, 0x3b808081, v223
	v_mul_f32_e32 v9, v49, v10
	v_rcp_f32_e32 v8, v8
	v_exp_f32_e32 v9, v9
	v_fmamk_f32 v7, v7, 0x3b808081, v223
	v_cvt_pk_u8_f32 v6, v6, 0, 0
	v_rcp_f32_e32 v7, v7
	v_cvt_pk_u8_f32 v6, v8, 1, v6
	v_fmamk_f32 v8, v9, 0x3b808081, v223
	v_mul_f32_e32 v9, v46, v10
	v_mul_f32_e32 v11, v50, v10
	v_rcp_f32_e32 v8, v8
	v_exp_f32_e32 v9, v9
	v_exp_f32_e32 v11, v11
	v_cvt_pk_u8_f32 v7, v7, 0, 0
	v_cvt_pk_u8_f32 v7, v8, 1, v7
	v_fmamk_f32 v8, v9, 0x3b808081, v223
	v_fmamk_f32 v9, v11, 0x3b808081, v223
	v_mul_f32_e32 v11, v47, v10
	v_exp_f32_e32 v11, v11
	v_rcp_f32_e32 v8, v8
	v_mul_f32_e32 v12, v51, v10
	v_exp_f32_e32 v12, v12
	v_fmamk_f32 v11, v11, 0x3b808081, v223
	v_rcp_f32_e32 v11, v11
	v_cvt_pk_u8_f32 v6, v8, 2, v6
	v_rcp_f32_e32 v9, v9
	v_fmamk_f32 v12, v12, 0x3b808081, v223
	v_cvt_pk_u8_f32 v6, v11, 3, v6
	v_add_u32_e32 v8, 0xfefefeff, v6
	v_bitop3_b32 v8, v8, v6, v8 bitop3:0x30
	v_lshrrev_b32_e32 v8, 7, v8
	v_and_or_b32 v6, v8, s9, v6
	v_mul_f32_e32 v8, v52, v10
	v_rcp_f32_e32 v12, v12
	v_exp_f32_e32 v8, v8
	v_cvt_pk_u8_f32 v7, v9, 2, v7
	v_mul_f32_e32 v11, v56, v10
	v_cvt_pk_u8_f32 v7, v12, 3, v7
	v_fmamk_f32 v8, v8, 0x3b808081, v223
	v_add_u32_e32 v9, 0xfefefeff, v7
	v_rcp_f32_e32 v8, v8
	v_bitop3_b32 v9, v9, v7, v9 bitop3:0x30
	v_lshrrev_b32_e32 v9, 7, v9
	v_and_or_b32 v7, v9, s9, v7
	v_exp_f32_e32 v11, v11
	global_store_dwordx2 v[14:15], v[6:7], off offset:2048
	v_cvt_pk_u8_f32 v6, v8, 0, 0
	v_mul_f32_e32 v8, v53, v10
	v_mul_f32_e32 v9, v57, v10
	v_exp_f32_e32 v8, v8
	v_exp_f32_e32 v9, v9
	v_fmamk_f32 v7, v11, 0x3b808081, v223
	v_rcp_f32_e32 v7, v7
	v_fmamk_f32 v8, v8, 0x3b808081, v223
	v_fmamk_f32 v9, v9, 0x3b808081, v223
	v_mul_f32_e32 v11, v54, v10
	s_waitcnt vmcnt(12)
	v_add_f32_e32 v2, v2, v3
	v_add_f32_e32 v3, v4, v5
	v_rcp_f32_e32 v8, v8
	v_rcp_f32_e32 v9, v9
	v_exp_f32_e32 v11, v11
	v_add_f32_e32 v2, v2, v3
	ds_bpermute_b32 v3, v181, v2
	v_cvt_pk_u8_f32 v7, v7, 0, 0
	v_cvt_pk_u8_f32 v6, v8, 1, v6
	v_cvt_pk_u8_f32 v7, v9, 1, v7
	v_fmamk_f32 v8, v11, 0x3b808081, v223
	v_mul_f32_e32 v9, v58, v10
	v_mul_f32_e32 v11, v55, v10
	v_rcp_f32_e32 v8, v8
	v_exp_f32_e32 v9, v9
	v_exp_f32_e32 v11, v11
	v_mul_f32_e32 v10, v59, v10
	v_exp_f32_e32 v10, v10
	s_waitcnt lgkmcnt(0)
	v_add_f32_e32 v2, v2, v3
	ds_bpermute_b32 v3, v180, v2
	v_cvt_pk_u8_f32 v6, v8, 2, v6
	v_fmamk_f32 v8, v9, 0x3b808081, v223
	v_fmamk_f32 v9, v11, 0x3b808081, v223
	v_rcp_f32_e32 v8, v8
	v_rcp_f32_e32 v9, v9
	v_fmamk_f32 v5, v10, 0x3b808081, v223
	v_rcp_f32_e32 v5, v5
	s_waitcnt lgkmcnt(0)
	v_add_f32_e32 v2, v2, v3
	v_fmamk_f32 v2, v2, 0x3a800000, v222
	v_cvt_pk_u8_f32 v4, v8, 2, v7
	v_cvt_pk_u8_f32 v6, v9, 3, v6
	v_rsq_f32_e32 v3, v2
	v_cvt_pk_u8_f32 v4, v5, 3, v4
	v_add_u32_e32 v5, 0xfefefeff, v6
	v_bitop3_b32 v5, v5, v6, v5 bitop3:0x30
	v_lshrrev_b32_e32 v5, 7, v5
	v_and_or_b32 v2, v5, s9, v6
	v_add_u32_e32 v5, 0xfefefeff, v4
	v_mul_f32_e32 v6, 0xbcb8aa3b, v3
	v_bitop3_b32 v5, v5, v4, v5 bitop3:0x30
	v_mul_f32_e32 v3, v28, v6
	v_exp_f32_e32 v7, v3
	v_lshrrev_b32_e32 v3, 7, v5
	v_and_or_b32 v3, v3, s9, v4
	v_mul_f32_e32 v4, v29, v6
	v_exp_f32_e32 v4, v4
	global_store_dwordx2 v[14:15], v[2:3], off offset:2560
	v_fmamk_f32 v2, v7, 0x3b808081, v223
	v_mul_f32_e32 v3, v32, v6
	v_exp_f32_e32 v3, v3
	v_rcp_f32_e32 v2, v2
	v_fmamk_f32 v4, v4, 0x3b808081, v223
	v_mul_f32_e32 v5, v33, v6
	v_rcp_f32_e32 v4, v4
	v_exp_f32_e32 v5, v5
	v_fmamk_f32 v3, v3, 0x3b808081, v223
	v_cvt_pk_u8_f32 v2, v2, 0, 0
	v_rcp_f32_e32 v3, v3
	v_cvt_pk_u8_f32 v2, v4, 1, v2
	v_fmamk_f32 v4, v5, 0x3b808081, v223
	v_mul_f32_e32 v5, v30, v6
	v_mul_f32_e32 v7, v34, v6
	v_rcp_f32_e32 v4, v4
	v_exp_f32_e32 v5, v5
	v_exp_f32_e32 v7, v7
	v_cvt_pk_u8_f32 v3, v3, 0, 0
	v_cvt_pk_u8_f32 v3, v4, 1, v3
	v_fmamk_f32 v4, v5, 0x3b808081, v223
	v_fmamk_f32 v5, v7, 0x3b808081, v223
	v_mul_f32_e32 v7, v31, v6
	v_exp_f32_e32 v7, v7
	v_mul_f32_e32 v8, v35, v6
	v_exp_f32_e32 v8, v8
	v_rcp_f32_e32 v4, v4
	v_fmamk_f32 v7, v7, 0x3b808081, v223
	v_rcp_f32_e32 v7, v7
	v_rcp_f32_e32 v5, v5
	v_fmamk_f32 v8, v8, 0x3b808081, v223
	v_rcp_f32_e32 v8, v8
	v_cvt_pk_u8_f32 v2, v4, 2, v2
	v_cvt_pk_u8_f32 v2, v7, 3, v2
	v_add_u32_e32 v4, 0xfefefeff, v2
	v_cvt_pk_u8_f32 v3, v5, 2, v3
	v_bitop3_b32 v4, v4, v2, v4 bitop3:0x30
	v_cvt_pk_u8_f32 v3, v8, 3, v3
	v_lshrrev_b32_e32 v4, 7, v4
	v_and_or_b32 v2, v4, s9, v2
	v_add_u32_e32 v4, 0xfefefeff, v3
	v_bitop3_b32 v4, v4, v3, v4 bitop3:0x30
	v_mul_f32_e32 v5, v36, v6
	v_lshrrev_b32_e32 v4, 7, v4
	v_exp_f32_e32 v5, v5
	v_and_or_b32 v3, v4, s9, v3
	v_mul_f32_e32 v4, v37, v6
	v_exp_f32_e32 v4, v4
	global_store_dwordx2 v[14:15], v[2:3], off offset:3072
	v_fmamk_f32 v2, v5, 0x3b808081, v223
	v_mul_f32_e32 v3, v40, v6
	v_exp_f32_e32 v3, v3
	v_rcp_f32_e32 v2, v2
	v_fmamk_f32 v4, v4, 0x3b808081, v223
	v_mul_f32_e32 v5, v41, v6
	v_rcp_f32_e32 v4, v4
	v_exp_f32_e32 v5, v5
	v_fmamk_f32 v3, v3, 0x3b808081, v223
	v_cvt_pk_u8_f32 v2, v2, 0, 0
	v_rcp_f32_e32 v3, v3
	v_cvt_pk_u8_f32 v2, v4, 1, v2
	v_fmamk_f32 v4, v5, 0x3b808081, v223
	v_mul_f32_e32 v5, v38, v6
	v_mul_f32_e32 v7, v42, v6
	v_rcp_f32_e32 v4, v4
	v_exp_f32_e32 v5, v5
	v_exp_f32_e32 v7, v7
	v_cvt_pk_u8_f32 v3, v3, 0, 0
	v_cvt_pk_u8_f32 v3, v4, 1, v3
	v_fmamk_f32 v4, v5, 0x3b808081, v223
	v_fmamk_f32 v5, v7, 0x3b808081, v223
	v_mul_f32_e32 v7, v39, v6
	v_exp_f32_e32 v7, v7
	v_mul_f32_e32 v6, v43, v6
	v_exp_f32_e32 v6, v6
	v_rcp_f32_e32 v4, v4
	v_fmamk_f32 v7, v7, 0x3b808081, v223
	v_rcp_f32_e32 v7, v7
	v_rcp_f32_e32 v5, v5
	v_fmamk_f32 v6, v6, 0x3b808081, v223
	v_rcp_f32_e32 v6, v6
	v_cvt_pk_u8_f32 v2, v4, 2, v2
	v_cvt_pk_u8_f32 v2, v7, 3, v2
	v_add_u32_e32 v4, 0xfefefeff, v2
	v_cvt_pk_u8_f32 v3, v5, 2, v3
	v_bitop3_b32 v4, v4, v2, v4 bitop3:0x30
	v_cvt_pk_u8_f32 v3, v6, 3, v3
	v_lshrrev_b32_e32 v4, 7, v4
	v_and_or_b32 v2, v4, s9, v2
	v_add_u32_e32 v4, 0xfefefeff, v3
	v_bitop3_b32 v4, v4, v3, v4 bitop3:0x30
	v_lshrrev_b32_e32 v4, 7, v4
	v_and_or_b32 v3, v4, s9, v3
	v_mov_b32_e32 v26, v27
	global_store_dwordx2 v[14:15], v[2:3], off offset:3584
	v_mov_b32_e32 v28, v27
	v_mov_b32_e32 v29, v27
	v_mov_b64_e32 v[2:3], v[26:27]
	v_mov_b64_e32 v[4:5], v[28:29]
	global_store_dwordx2 v[178:179], v[140:141], off offset:512
	v_readlane_b32 s54, v250, 19
	s_and_b64 vcc, exec, s[0:1]
	s_mov_b64 s[0:1], -1
	v_readlane_b32 s55, v250, 20
	s_cbranch_vccnz .LBB0_379
	s_andn2_b64 vcc, exec, s[28:29]
	s_cbranch_vccnz .LBB0_378
	s_barrier
	s_branch .LBB0_378
